# v67 plus MLP2A/B and OUT1 full tiles (256x128, schedule unchanged) hand-written with 16x16x32 MFMA, pipelined K loop, bias in accumulator init
# baseline (speedup 1.0000x reference)
.LBB0_55:
	s_waitcnt lgkmcnt(0)
	s_lshl_b64 s[36:37], s[28:29], 13
	s_add_u32 s36, s36, s34
	s_addc_u32 s37, s37, s35
	s_lshl_b32 vcc_hi, s52, 3
	s_sub_i32 vcc_hi, s24, vcc_hi
	s_lshl_b32 s28, vcc_hi, 7
	s_lshl_b32 vcc_hi, s28, 13
	s_add_u32 s98, s50, vcc_hi
	s_addc_u32 s99, s51, 0
	v_readfirstlane_b32 vcc_hi, v200
	s_lshr_b32 vcc_hi, vcc_hi, 6
	s_lshl_b32 s25, vcc_hi, 11
	s_add_u32 s25, s25, 16
	s_lshl_b32 s31, vcc_hi, 10
	s_add_u32 s31, s31, 0x4010
	s_lshl_b32 vcc_hi, vcc_hi, 17
	s_add_u32 s98, s98, vcc_hi
	s_addc_u32 s99, s99, 0
	s_lshl_b32 vcc_hi, vcc_hi, 1
	s_add_u32 s36, s36, vcc_hi
	s_addc_u32 s37, s37, 0
	v_bfe_u32 v173, v200, 4, 2
	v_sub_u32_e32 v173, 0, v173
	v_and_b32_e32 v173, 3, v173
	v_and_b32_e32 v172, 3, v200
	v_xor_b32_e32 v172, v172, v173
	v_bfe_u32 v173, v200, 2, 4
	v_lshlrev_b32_e32 v173, 13, v173
	v_lshl_or_b32 v170, v172, 4, v173
	v_add_u32_e32 v171, 0x20000, v170
	v_bfe_u32 v172, v200, 2, 2
	v_sub_u32_e32 v172, 0, v172
	v_and_b32_e32 v172, 3, v172
	v_bfe_u32 v173, v200, 4, 2
	v_xor_b32_e32 v172, v172, v173
	v_and_b32_e32 v173, 15, v200
	v_bfe_u32 v174, v200, 7, 2
	v_lshl_or_b32 v174, v174, 6, v173
	v_lshlrev_b32_e32 v174, 6, v174
	v_lshl_or_b32 v164, v172, 4, v174
	v_bfe_u32 v174, v200, 6, 1
	v_lshl_or_b32 v174, v174, 6, v173
	v_lshlrev_b32_e32 v174, 6, v174
	v_lshl_or_b32 v165, v172, 4, v174
	v_add_u32_e32 v165, 0x4000, v165
	v_bfe_u32 v172, v200, 6, 1
	v_bfe_u32 v173, v200, 4, 2
	v_lshlrev_b32_e32 v172, 6, v172
	v_lshl_or_b32 v172, v173, 2, v172
	v_add_u32_e32 v172, s28, v172
	v_lshlrev_b32_e32 v172, 2, v172
	global_load_dwordx4 v[132:135], v172, s[44:45]
	global_load_dwordx4 v[136:139], v172, s[44:45] offset:64
	global_load_dwordx4 v[140:143], v172, s[44:45] offset:128
	global_load_dwordx4 v[144:147], v172, s[44:45] offset:192
	s_mov_b32 s53, 0x0
	s_add_u32 m0, s25, s53
	s_nop 0
	global_load_lds_dwordx4 v170, s[36:37]
	s_add_u32 m0, s25, s53
	s_add_u32 m0, m0, 0x400
	s_nop 0
	global_load_lds_dwordx4 v171, s[36:37]
	s_add_u32 m0, s31, s53
	s_nop 0
	global_load_lds_dwordx4 v170, s[98:99]
	s_add_u32 s36, s36, 64
	s_addc_u32 s37, s37, 0
	s_add_u32 s98, s98, 64
	s_addc_u32 s99, s99, 0
	s_mov_b32 s53, 0x6000
	s_add_u32 m0, s25, s53
	s_nop 0
	global_load_lds_dwordx4 v170, s[36:37]
	s_add_u32 m0, s25, s53
	s_add_u32 m0, m0, 0x400
	s_nop 0
	global_load_lds_dwordx4 v171, s[36:37]
	s_add_u32 m0, s31, s53
	s_nop 0
	global_load_lds_dwordx4 v170, s[98:99]
	s_add_u32 s36, s36, 64
	s_addc_u32 s37, s37, 0
	s_add_u32 s98, s98, 64
	s_addc_u32 s99, s99, 0
	s_mov_b32 s53, 0xc000
	s_add_u32 m0, s25, s53
	s_nop 0
	global_load_lds_dwordx4 v170, s[36:37]
	s_add_u32 m0, s25, s53
	s_add_u32 m0, m0, 0x400
	s_nop 0
	global_load_lds_dwordx4 v171, s[36:37]
	s_add_u32 m0, s31, s53
	s_nop 0
	global_load_lds_dwordx4 v170, s[98:99]
	s_add_u32 s36, s36, 64
	s_addc_u32 s37, s37, 0
	s_add_u32 s98, s98, 64
	s_addc_u32 s99, s99, 0
	s_mov_b32 s53, 0x12000
	s_add_u32 m0, s25, s53
	s_nop 0
	global_load_lds_dwordx4 v170, s[36:37]
	s_add_u32 m0, s25, s53
	s_add_u32 m0, m0, 0x400
	s_nop 0
	global_load_lds_dwordx4 v171, s[36:37]
	s_add_u32 m0, s31, s53
	s_nop 0
	global_load_lds_dwordx4 v170, s[98:99]
	s_add_u32 s36, s36, 64
	s_addc_u32 s37, s37, 0
	s_add_u32 s98, s98, 64
	s_addc_u32 s99, s99, 0
	s_waitcnt vmcnt(12)
	v_mov_b32_e32 v4, v132
	v_mov_b32_e32 v5, v133
	v_mov_b32_e32 v6, v134
	v_mov_b32_e32 v7, v135
	v_mov_b32_e32 v8, v136
	v_mov_b32_e32 v9, v137
	v_mov_b32_e32 v10, v138
	v_mov_b32_e32 v11, v139
	v_mov_b32_e32 v12, v140
	v_mov_b32_e32 v13, v141
	v_mov_b32_e32 v14, v142
	v_mov_b32_e32 v15, v143
	v_mov_b32_e32 v16, v144
	v_mov_b32_e32 v17, v145
	v_mov_b32_e32 v18, v146
	v_mov_b32_e32 v19, v147
	v_mov_b32_e32 v20, v132
	v_mov_b32_e32 v21, v133
	v_mov_b32_e32 v22, v134
	v_mov_b32_e32 v23, v135
	v_mov_b32_e32 v24, v136
	v_mov_b32_e32 v25, v137
	v_mov_b32_e32 v26, v138
	v_mov_b32_e32 v27, v139
	v_mov_b32_e32 v28, v140
	v_mov_b32_e32 v29, v141
	v_mov_b32_e32 v30, v142
	v_mov_b32_e32 v31, v143
	v_mov_b32_e32 v32, v144
	v_mov_b32_e32 v33, v145
	v_mov_b32_e32 v34, v146
	v_mov_b32_e32 v35, v147
	v_mov_b32_e32 v36, v132
	v_mov_b32_e32 v37, v133
	v_mov_b32_e32 v38, v134
	v_mov_b32_e32 v39, v135
	v_mov_b32_e32 v40, v136
	v_mov_b32_e32 v41, v137
	v_mov_b32_e32 v42, v138
	v_mov_b32_e32 v43, v139
	v_mov_b32_e32 v44, v140
	v_mov_b32_e32 v45, v141
	v_mov_b32_e32 v46, v142
	v_mov_b32_e32 v47, v143
	v_mov_b32_e32 v48, v144
	v_mov_b32_e32 v49, v145
	v_mov_b32_e32 v50, v146
	v_mov_b32_e32 v51, v147
	v_mov_b32_e32 v52, v132
	v_mov_b32_e32 v53, v133
	v_mov_b32_e32 v54, v134
	v_mov_b32_e32 v55, v135
	v_mov_b32_e32 v56, v136
	v_mov_b32_e32 v57, v137
	v_mov_b32_e32 v58, v138
	v_mov_b32_e32 v59, v139
	v_mov_b32_e32 v60, v140
	v_mov_b32_e32 v61, v141
	v_mov_b32_e32 v62, v142
	v_mov_b32_e32 v63, v143
	v_mov_b32_e32 v64, v144
	v_mov_b32_e32 v65, v145
	v_mov_b32_e32 v66, v146
	v_mov_b32_e32 v67, v147
	s_waitcnt vmcnt(9)
	s_barrier
	s_mov_b32 s32, 0
	s_mov_b32 s65, 0
	s_nop 1
	v_add_u32_e32 v168, s32, v165
	v_add_u32_e32 v169, s32, v164
	ds_read_b128 v[132:135], v168 offset:16
	ds_read_b128 v[136:139], v168 offset:1040
	ds_read_b128 v[140:143], v168 offset:2064
	ds_read_b128 v[144:147], v168 offset:3088
	ds_read_b128 v[184:187], v169 offset:16
	ds_read_b128 v[188:191], v169 offset:1040
	s_waitcnt lgkmcnt(0)
.Lt_mlp2bn:
	v_add_u32_e32 v169, s32, v164
	v_mfma_f32_16x16x32_f16 v[4:7], v[132:135], v[184:187], v[4:7]
	ds_read_b128 v[192:195], v169 offset:2064
	v_mfma_f32_16x16x32_f16 v[8:11], v[136:139], v[184:187], v[8:11]
	ds_read_b128 v[196:199], v169 offset:3088
	v_mfma_f32_16x16x32_f16 v[12:15], v[140:143], v[184:187], v[12:15]
	v_mfma_f32_16x16x32_f16 v[16:19], v[144:147], v[184:187], v[16:19]
	v_mfma_f32_16x16x32_f16 v[20:23], v[132:135], v[188:191], v[20:23]
	v_mfma_f32_16x16x32_f16 v[24:27], v[136:139], v[188:191], v[24:27]
	v_mfma_f32_16x16x32_f16 v[28:31], v[140:143], v[188:191], v[28:31]
	v_mfma_f32_16x16x32_f16 v[32:35], v[144:147], v[188:191], v[32:35]
	s_waitcnt vmcnt(6) lgkmcnt(0)
	s_barrier
	s_add_i32 s53, s32, 0x6000
	s_cmp_lg_u32 s32, 0x12000
	s_cselect_b32 s53, s53, 0
	v_add_u32_e32 v168, s53, v165
	v_add_u32_e32 v169, s53, v164
	v_mfma_f32_16x16x32_f16 v[36:39], v[132:135], v[192:195], v[36:39]
	ds_read_b128 v[148:151], v168 offset:16
	ds_read_b128 v[184:187], v169 offset:16
	v_mfma_f32_16x16x32_f16 v[40:43], v[136:139], v[192:195], v[40:43]
	ds_read_b128 v[152:155], v168 offset:1040
	ds_read_b128 v[188:191], v169 offset:1040
	v_mfma_f32_16x16x32_f16 v[44:47], v[140:143], v[192:195], v[44:47]
	ds_read_b128 v[156:159], v168 offset:2064
	v_mfma_f32_16x16x32_f16 v[48:51], v[144:147], v[192:195], v[48:51]
	ds_read_b128 v[160:163], v168 offset:3088
	v_mfma_f32_16x16x32_f16 v[52:55], v[132:135], v[196:199], v[52:55]
	s_add_u32 m0, s25, s32
	s_nop 0
	global_load_lds_dwordx4 v170, s[36:37]
	v_mfma_f32_16x16x32_f16 v[56:59], v[136:139], v[196:199], v[56:59]
	s_add_u32 m0, s25, s32
	s_add_u32 m0, m0, 0x400
	s_nop 0
	global_load_lds_dwordx4 v171, s[36:37]
	v_mfma_f32_16x16x32_f16 v[60:63], v[140:143], v[196:199], v[60:63]
	s_add_u32 m0, s31, s32
	s_nop 0
	global_load_lds_dwordx4 v170, s[98:99]
	v_mfma_f32_16x16x32_f16 v[64:67], v[144:147], v[196:199], v[64:67]
	s_waitcnt lgkmcnt(0)
	s_mov_b32 s32, s53
	s_add_u32 s36, s36, 64
	s_addc_u32 s37, s37, 0
	s_add_u32 s98, s98, 64
	s_addc_u32 s99, s99, 0
	v_add_u32_e32 v169, s32, v164
	v_mfma_f32_16x16x32_f16 v[4:7], v[148:151], v[184:187], v[4:7]
	ds_read_b128 v[192:195], v169 offset:2064
	v_mfma_f32_16x16x32_f16 v[8:11], v[152:155], v[184:187], v[8:11]
	ds_read_b128 v[196:199], v169 offset:3088
	v_mfma_f32_16x16x32_f16 v[12:15], v[156:159], v[184:187], v[12:15]
	v_mfma_f32_16x16x32_f16 v[16:19], v[160:163], v[184:187], v[16:19]
	v_mfma_f32_16x16x32_f16 v[20:23], v[148:151], v[188:191], v[20:23]
	v_mfma_f32_16x16x32_f16 v[24:27], v[152:155], v[188:191], v[24:27]
	v_mfma_f32_16x16x32_f16 v[28:31], v[156:159], v[188:191], v[28:31]
	v_mfma_f32_16x16x32_f16 v[32:35], v[160:163], v[188:191], v[32:35]
	s_waitcnt vmcnt(6) lgkmcnt(0)
	s_barrier
	s_add_i32 s53, s32, 0x6000
	s_cmp_lg_u32 s32, 0x12000
	s_cselect_b32 s53, s53, 0
	v_add_u32_e32 v168, s53, v165
	v_add_u32_e32 v169, s53, v164
	v_mfma_f32_16x16x32_f16 v[36:39], v[148:151], v[192:195], v[36:39]
	ds_read_b128 v[132:135], v168 offset:16
	ds_read_b128 v[184:187], v169 offset:16
	v_mfma_f32_16x16x32_f16 v[40:43], v[152:155], v[192:195], v[40:43]
	ds_read_b128 v[136:139], v168 offset:1040
	ds_read_b128 v[188:191], v169 offset:1040
	v_mfma_f32_16x16x32_f16 v[44:47], v[156:159], v[192:195], v[44:47]
	ds_read_b128 v[140:143], v168 offset:2064
	v_mfma_f32_16x16x32_f16 v[48:51], v[160:163], v[192:195], v[48:51]
	ds_read_b128 v[144:147], v168 offset:3088
	v_mfma_f32_16x16x32_f16 v[52:55], v[148:151], v[196:199], v[52:55]
	s_add_u32 m0, s25, s32
	s_nop 0
	global_load_lds_dwordx4 v170, s[36:37]
	v_mfma_f32_16x16x32_f16 v[56:59], v[152:155], v[196:199], v[56:59]
	s_add_u32 m0, s25, s32
	s_add_u32 m0, m0, 0x400
	s_nop 0
	global_load_lds_dwordx4 v171, s[36:37]
	v_mfma_f32_16x16x32_f16 v[60:63], v[156:159], v[196:199], v[60:63]
	s_add_u32 m0, s31, s32
	s_nop 0
	global_load_lds_dwordx4 v170, s[98:99]
	v_mfma_f32_16x16x32_f16 v[64:67], v[160:163], v[196:199], v[64:67]
	s_waitcnt lgkmcnt(0)
	s_mov_b32 s32, s53
	s_add_u32 s36, s36, 64
	s_addc_u32 s37, s37, 0
	s_add_u32 s98, s98, 64
	s_addc_u32 s99, s99, 0
	s_add_i32 s65, s65, 2
	s_cmp_lt_u32 s65, 124
	s_cbranch_scc1 .Lt_mlp2bn
	v_add_u32_e32 v169, s32, v164
	v_mfma_f32_16x16x32_f16 v[4:7], v[132:135], v[184:187], v[4:7]
	ds_read_b128 v[192:195], v169 offset:2064
	v_mfma_f32_16x16x32_f16 v[8:11], v[136:139], v[184:187], v[8:11]
	ds_read_b128 v[196:199], v169 offset:3088
	v_mfma_f32_16x16x32_f16 v[12:15], v[140:143], v[184:187], v[12:15]
	v_mfma_f32_16x16x32_f16 v[16:19], v[144:147], v[184:187], v[16:19]
	v_mfma_f32_16x16x32_f16 v[20:23], v[132:135], v[188:191], v[20:23]
	v_mfma_f32_16x16x32_f16 v[24:27], v[136:139], v[188:191], v[24:27]
	v_mfma_f32_16x16x32_f16 v[28:31], v[140:143], v[188:191], v[28:31]
	v_mfma_f32_16x16x32_f16 v[32:35], v[144:147], v[188:191], v[32:35]
	s_waitcnt vmcnt(6) lgkmcnt(0)
	s_barrier
	s_add_i32 s53, s32, 0x6000
	s_cmp_lg_u32 s32, 0x12000
	s_cselect_b32 s53, s53, 0
	v_add_u32_e32 v168, s53, v165
	v_add_u32_e32 v169, s53, v164
	v_mfma_f32_16x16x32_f16 v[36:39], v[132:135], v[192:195], v[36:39]
	ds_read_b128 v[148:151], v168 offset:16
	ds_read_b128 v[184:187], v169 offset:16
	v_mfma_f32_16x16x32_f16 v[40:43], v[136:139], v[192:195], v[40:43]
	ds_read_b128 v[152:155], v168 offset:1040
	ds_read_b128 v[188:191], v169 offset:1040
	v_mfma_f32_16x16x32_f16 v[44:47], v[140:143], v[192:195], v[44:47]
	ds_read_b128 v[156:159], v168 offset:2064
	v_mfma_f32_16x16x32_f16 v[48:51], v[144:147], v[192:195], v[48:51]
	ds_read_b128 v[160:163], v168 offset:3088
	v_mfma_f32_16x16x32_f16 v[52:55], v[132:135], v[196:199], v[52:55]
	v_mfma_f32_16x16x32_f16 v[56:59], v[136:139], v[196:199], v[56:59]
	v_mfma_f32_16x16x32_f16 v[60:63], v[140:143], v[196:199], v[60:63]
	v_mfma_f32_16x16x32_f16 v[64:67], v[144:147], v[196:199], v[64:67]
	s_waitcnt lgkmcnt(0)
	s_mov_b32 s32, s53
	v_add_u32_e32 v169, s32, v164
	v_mfma_f32_16x16x32_f16 v[4:7], v[148:151], v[184:187], v[4:7]
	ds_read_b128 v[192:195], v169 offset:2064
	v_mfma_f32_16x16x32_f16 v[8:11], v[152:155], v[184:187], v[8:11]
	ds_read_b128 v[196:199], v169 offset:3088
	v_mfma_f32_16x16x32_f16 v[12:15], v[156:159], v[184:187], v[12:15]
	v_mfma_f32_16x16x32_f16 v[16:19], v[160:163], v[184:187], v[16:19]
	v_mfma_f32_16x16x32_f16 v[20:23], v[148:151], v[188:191], v[20:23]
	v_mfma_f32_16x16x32_f16 v[24:27], v[152:155], v[188:191], v[24:27]
	v_mfma_f32_16x16x32_f16 v[28:31], v[156:159], v[188:191], v[28:31]
	v_mfma_f32_16x16x32_f16 v[32:35], v[160:163], v[188:191], v[32:35]
	s_waitcnt vmcnt(3) lgkmcnt(0)
	s_barrier
	s_add_i32 s53, s32, 0x6000
	s_cmp_lg_u32 s32, 0x12000
	s_cselect_b32 s53, s53, 0
	v_add_u32_e32 v168, s53, v165
	v_add_u32_e32 v169, s53, v164
	v_mfma_f32_16x16x32_f16 v[36:39], v[148:151], v[192:195], v[36:39]
	ds_read_b128 v[132:135], v168 offset:16
	ds_read_b128 v[184:187], v169 offset:16
	v_mfma_f32_16x16x32_f16 v[40:43], v[152:155], v[192:195], v[40:43]
	ds_read_b128 v[136:139], v168 offset:1040
	ds_read_b128 v[188:191], v169 offset:1040
	v_mfma_f32_16x16x32_f16 v[44:47], v[156:159], v[192:195], v[44:47]
	ds_read_b128 v[140:143], v168 offset:2064
	v_mfma_f32_16x16x32_f16 v[48:51], v[160:163], v[192:195], v[48:51]
	ds_read_b128 v[144:147], v168 offset:3088
	v_mfma_f32_16x16x32_f16 v[52:55], v[148:151], v[196:199], v[52:55]
	v_mfma_f32_16x16x32_f16 v[56:59], v[152:155], v[196:199], v[56:59]
	v_mfma_f32_16x16x32_f16 v[60:63], v[156:159], v[196:199], v[60:63]
	v_mfma_f32_16x16x32_f16 v[64:67], v[160:163], v[196:199], v[64:67]
	s_waitcnt lgkmcnt(0)
	s_mov_b32 s32, s53
	v_add_u32_e32 v169, s32, v164
	v_mfma_f32_16x16x32_f16 v[4:7], v[132:135], v[184:187], v[4:7]
	ds_read_b128 v[192:195], v169 offset:2064
	v_mfma_f32_16x16x32_f16 v[8:11], v[136:139], v[184:187], v[8:11]
	ds_read_b128 v[196:199], v169 offset:3088
	v_mfma_f32_16x16x32_f16 v[12:15], v[140:143], v[184:187], v[12:15]
	v_mfma_f32_16x16x32_f16 v[16:19], v[144:147], v[184:187], v[16:19]
	v_mfma_f32_16x16x32_f16 v[20:23], v[132:135], v[188:191], v[20:23]
	v_mfma_f32_16x16x32_f16 v[24:27], v[136:139], v[188:191], v[24:27]
	v_mfma_f32_16x16x32_f16 v[28:31], v[140:143], v[188:191], v[28:31]
	v_mfma_f32_16x16x32_f16 v[32:35], v[144:147], v[188:191], v[32:35]
	s_waitcnt vmcnt(0) lgkmcnt(0)
	s_barrier
	s_add_i32 s53, s32, 0x6000
	s_cmp_lg_u32 s32, 0x12000
	s_cselect_b32 s53, s53, 0
	v_add_u32_e32 v168, s53, v165
	v_add_u32_e32 v169, s53, v164
	v_mfma_f32_16x16x32_f16 v[36:39], v[132:135], v[192:195], v[36:39]
	ds_read_b128 v[148:151], v168 offset:16
	ds_read_b128 v[184:187], v169 offset:16
	v_mfma_f32_16x16x32_f16 v[40:43], v[136:139], v[192:195], v[40:43]
	ds_read_b128 v[152:155], v168 offset:1040
	ds_read_b128 v[188:191], v169 offset:1040
	v_mfma_f32_16x16x32_f16 v[44:47], v[140:143], v[192:195], v[44:47]
	ds_read_b128 v[156:159], v168 offset:2064
	v_mfma_f32_16x16x32_f16 v[48:51], v[144:147], v[192:195], v[48:51]
	ds_read_b128 v[160:163], v168 offset:3088
	v_mfma_f32_16x16x32_f16 v[52:55], v[132:135], v[196:199], v[52:55]
	v_mfma_f32_16x16x32_f16 v[56:59], v[136:139], v[196:199], v[56:59]
	v_mfma_f32_16x16x32_f16 v[60:63], v[140:143], v[196:199], v[60:63]
	v_mfma_f32_16x16x32_f16 v[64:67], v[144:147], v[196:199], v[64:67]
	s_waitcnt lgkmcnt(0)
	s_mov_b32 s32, s53
	v_add_u32_e32 v169, s32, v164
	v_mfma_f32_16x16x32_f16 v[4:7], v[148:151], v[184:187], v[4:7]
	ds_read_b128 v[192:195], v169 offset:2064
	v_mfma_f32_16x16x32_f16 v[8:11], v[152:155], v[184:187], v[8:11]
	ds_read_b128 v[196:199], v169 offset:3088
	v_mfma_f32_16x16x32_f16 v[12:15], v[156:159], v[184:187], v[12:15]
	v_mfma_f32_16x16x32_f16 v[16:19], v[160:163], v[184:187], v[16:19]
	v_mfma_f32_16x16x32_f16 v[20:23], v[148:151], v[188:191], v[20:23]
	v_mfma_f32_16x16x32_f16 v[24:27], v[152:155], v[188:191], v[24:27]
	v_mfma_f32_16x16x32_f16 v[28:31], v[156:159], v[188:191], v[28:31]
	v_mfma_f32_16x16x32_f16 v[32:35], v[160:163], v[188:191], v[32:35]
	s_waitcnt lgkmcnt(0)
	s_barrier
	v_mfma_f32_16x16x32_f16 v[36:39], v[148:151], v[192:195], v[36:39]
	v_mfma_f32_16x16x32_f16 v[40:43], v[152:155], v[192:195], v[40:43]
	v_mfma_f32_16x16x32_f16 v[44:47], v[156:159], v[192:195], v[44:47]
	v_mfma_f32_16x16x32_f16 v[48:51], v[160:163], v[192:195], v[48:51]
	v_mfma_f32_16x16x32_f16 v[52:55], v[148:151], v[196:199], v[52:55]
	v_mfma_f32_16x16x32_f16 v[56:59], v[152:155], v[196:199], v[56:59]
	v_mfma_f32_16x16x32_f16 v[60:63], v[156:159], v[196:199], v[60:63]
	v_mfma_f32_16x16x32_f16 v[64:67], v[160:163], v[196:199], v[64:67]
	s_sub_u32 s77, s30, 0x1000
	s_lshr_b32 s77, s77, 12
	s_add_u32 s77, s77, 1
	s_cmp_lt_u32 s30, 0x1000
	s_cselect_b32 s77, 0, s77
	s_mul_i32 s77, s77, 0x6000
	s_add_u32 s68, s46, s77
	s_addc_u32 s69, s47, 0
	s_add_u32 s68, s68, 0xfa2e600
	s_addc_u32 s69, s69, 0
	s_lshl_b32 s82, s30, 11
	s_add_u32 s80, s48, s82
	s_addc_u32 s81, s49, 0
	s_lshl_b32 s82, s28, 1
	s_add_u32 s80, s80, s82
	s_addc_u32 s81, s81, 0
	v_and_b32_e32 v172, 15, v200
	v_bfe_u32 v173, v200, 4, 2
	v_bfe_u32 v174, v200, 6, 1
	v_bfe_u32 v175, v200, 7, 2
	v_lshlrev_b32_e32 v176, 6, v174
	v_lshl_or_b32 v176, v173, 2, v176
	v_lshl_or_b32 v175, v175, 6, v172
	v_lshlrev_b32_e32 v175, 11, v175
	v_lshl_add_u32 v177, v176, 1, v175
	v_add_u32_e32 v176, s28, v176
	v_lshlrev_b32_e32 v176, 2, v176
	global_load_dwordx4 v[132:135], v176, s[68:69]
	global_load_dwordx4 v[136:139], v176, s[68:69] offset:64
	global_load_dwordx4 v[140:143], v176, s[68:69] offset:128
	global_load_dwordx4 v[144:147], v176, s[68:69] offset:192
	v_mov_b32_e32 v178, v177
	global_load_dwordx2 v[184:185], v178, s[80:81]
	global_load_dwordx2 v[186:187], v178, s[80:81] offset:32
	global_load_dwordx2 v[188:189], v178, s[80:81] offset:64
	global_load_dwordx2 v[190:191], v178, s[80:81] offset:96
	v_add_u32_e32 v178, 0x8000, v178
	global_load_dwordx2 v[192:193], v178, s[80:81]
	global_load_dwordx2 v[194:195], v178, s[80:81] offset:32
	global_load_dwordx2 v[196:197], v178, s[80:81] offset:64
	global_load_dwordx2 v[198:199], v178, s[80:81] offset:96
	s_waitcnt vmcnt(7)
	v_cvt_f32_f16_e32 v164, v184
	v_cvt_f32_f16_sdwa v165, v184 dst_sel:DWORD dst_unused:UNUSED_PAD src0_sel:WORD_1
	v_cvt_f32_f16_e32 v166, v185
	v_cvt_f32_f16_sdwa v167, v185 dst_sel:DWORD dst_unused:UNUSED_PAD src0_sel:WORD_1
	v_pk_mul_f32 v[164:165], v[164:165], s[84:85] op_sel_hi:[1,0]
	v_pk_mul_f32 v[166:167], v[166:167], s[84:85] op_sel_hi:[1,0]
	v_pk_fma_f32 v[4:5], v[4:5], v[132:133], v[164:165]
	v_pk_fma_f32 v[6:7], v[6:7], v[134:135], v[166:167]
	v_cvt_pk_f16_f32 v172, v4, v5
	v_cvt_pk_f16_f32 v173, v6, v7
	global_store_dwordx2 v177, v[172:173], s[80:81]
	s_waitcnt vmcnt(7)
	v_cvt_f32_f16_e32 v164, v186
	v_cvt_f32_f16_sdwa v165, v186 dst_sel:DWORD dst_unused:UNUSED_PAD src0_sel:WORD_1
	v_cvt_f32_f16_e32 v166, v187
	v_cvt_f32_f16_sdwa v167, v187 dst_sel:DWORD dst_unused:UNUSED_PAD src0_sel:WORD_1
	v_pk_mul_f32 v[164:165], v[164:165], s[84:85] op_sel_hi:[1,0]
	v_pk_mul_f32 v[166:167], v[166:167], s[84:85] op_sel_hi:[1,0]
	v_pk_fma_f32 v[8:9], v[8:9], v[136:137], v[164:165]
	v_pk_fma_f32 v[10:11], v[10:11], v[138:139], v[166:167]
	v_cvt_pk_f16_f32 v174, v8, v9
	v_cvt_pk_f16_f32 v175, v10, v11
	global_store_dwordx2 v177, v[174:175], s[80:81] offset:32
	s_waitcnt vmcnt(7)
	v_cvt_f32_f16_e32 v164, v188
	v_cvt_f32_f16_sdwa v165, v188 dst_sel:DWORD dst_unused:UNUSED_PAD src0_sel:WORD_1
	v_cvt_f32_f16_e32 v166, v189
	v_cvt_f32_f16_sdwa v167, v189 dst_sel:DWORD dst_unused:UNUSED_PAD src0_sel:WORD_1
	v_pk_mul_f32 v[164:165], v[164:165], s[84:85] op_sel_hi:[1,0]
	v_pk_mul_f32 v[166:167], v[166:167], s[84:85] op_sel_hi:[1,0]
	v_pk_fma_f32 v[12:13], v[12:13], v[140:141], v[164:165]
	v_pk_fma_f32 v[14:15], v[14:15], v[142:143], v[166:167]
	v_cvt_pk_f16_f32 v172, v12, v13
	v_cvt_pk_f16_f32 v173, v14, v15
	global_store_dwordx2 v177, v[172:173], s[80:81] offset:64
	s_waitcnt vmcnt(7)
	v_cvt_f32_f16_e32 v164, v190
	v_cvt_f32_f16_sdwa v165, v190 dst_sel:DWORD dst_unused:UNUSED_PAD src0_sel:WORD_1
	v_cvt_f32_f16_e32 v166, v191
	v_cvt_f32_f16_sdwa v167, v191 dst_sel:DWORD dst_unused:UNUSED_PAD src0_sel:WORD_1
	v_pk_mul_f32 v[164:165], v[164:165], s[84:85] op_sel_hi:[1,0]
	v_pk_mul_f32 v[166:167], v[166:167], s[84:85] op_sel_hi:[1,0]
	v_pk_fma_f32 v[16:17], v[16:17], v[144:145], v[164:165]
	v_pk_fma_f32 v[18:19], v[18:19], v[146:147], v[166:167]
	v_cvt_pk_f16_f32 v174, v16, v17
	v_cvt_pk_f16_f32 v175, v18, v19
	global_store_dwordx2 v177, v[174:175], s[80:81] offset:96
	v_add_u32_e32 v177, 0x8000, v177
	v_add_u32_e32 v178, 0x8000, v178
	global_load_dwordx2 v[184:185], v178, s[80:81]
	global_load_dwordx2 v[186:187], v178, s[80:81] offset:32
	global_load_dwordx2 v[188:189], v178, s[80:81] offset:64
	global_load_dwordx2 v[190:191], v178, s[80:81] offset:96
	s_waitcnt vmcnt(11)
	v_cvt_f32_f16_e32 v164, v192
	v_cvt_f32_f16_sdwa v165, v192 dst_sel:DWORD dst_unused:UNUSED_PAD src0_sel:WORD_1
	v_cvt_f32_f16_e32 v166, v193
	v_cvt_f32_f16_sdwa v167, v193 dst_sel:DWORD dst_unused:UNUSED_PAD src0_sel:WORD_1
	v_pk_mul_f32 v[164:165], v[164:165], s[84:85] op_sel_hi:[1,0]
	v_pk_mul_f32 v[166:167], v[166:167], s[84:85] op_sel_hi:[1,0]
	v_pk_fma_f32 v[20:21], v[20:21], v[132:133], v[164:165]
	v_pk_fma_f32 v[22:23], v[22:23], v[134:135], v[166:167]
	v_cvt_pk_f16_f32 v172, v20, v21
	v_cvt_pk_f16_f32 v173, v22, v23
	global_store_dwordx2 v177, v[172:173], s[80:81]
	s_waitcnt vmcnt(11)
	v_cvt_f32_f16_e32 v164, v194
	v_cvt_f32_f16_sdwa v165, v194 dst_sel:DWORD dst_unused:UNUSED_PAD src0_sel:WORD_1
	v_cvt_f32_f16_e32 v166, v195
	v_cvt_f32_f16_sdwa v167, v195 dst_sel:DWORD dst_unused:UNUSED_PAD src0_sel:WORD_1
	v_pk_mul_f32 v[164:165], v[164:165], s[84:85] op_sel_hi:[1,0]
	v_pk_mul_f32 v[166:167], v[166:167], s[84:85] op_sel_hi:[1,0]
	v_pk_fma_f32 v[24:25], v[24:25], v[136:137], v[164:165]
	v_pk_fma_f32 v[26:27], v[26:27], v[138:139], v[166:167]
	v_cvt_pk_f16_f32 v174, v24, v25
	v_cvt_pk_f16_f32 v175, v26, v27
	global_store_dwordx2 v177, v[174:175], s[80:81] offset:32
	s_waitcnt vmcnt(11)
	v_cvt_f32_f16_e32 v164, v196
	v_cvt_f32_f16_sdwa v165, v196 dst_sel:DWORD dst_unused:UNUSED_PAD src0_sel:WORD_1
	v_cvt_f32_f16_e32 v166, v197
	v_cvt_f32_f16_sdwa v167, v197 dst_sel:DWORD dst_unused:UNUSED_PAD src0_sel:WORD_1
	v_pk_mul_f32 v[164:165], v[164:165], s[84:85] op_sel_hi:[1,0]
	v_pk_mul_f32 v[166:167], v[166:167], s[84:85] op_sel_hi:[1,0]
	v_pk_fma_f32 v[28:29], v[28:29], v[140:141], v[164:165]
	v_pk_fma_f32 v[30:31], v[30:31], v[142:143], v[166:167]
	v_cvt_pk_f16_f32 v172, v28, v29
	v_cvt_pk_f16_f32 v173, v30, v31
	global_store_dwordx2 v177, v[172:173], s[80:81] offset:64
	s_waitcnt vmcnt(11)
	v_cvt_f32_f16_e32 v164, v198
	v_cvt_f32_f16_sdwa v165, v198 dst_sel:DWORD dst_unused:UNUSED_PAD src0_sel:WORD_1
	v_cvt_f32_f16_e32 v166, v199
	v_cvt_f32_f16_sdwa v167, v199 dst_sel:DWORD dst_unused:UNUSED_PAD src0_sel:WORD_1
	v_pk_mul_f32 v[164:165], v[164:165], s[84:85] op_sel_hi:[1,0]
	v_pk_mul_f32 v[166:167], v[166:167], s[84:85] op_sel_hi:[1,0]
	v_pk_fma_f32 v[32:33], v[32:33], v[144:145], v[164:165]
	v_pk_fma_f32 v[34:35], v[34:35], v[146:147], v[166:167]
	v_cvt_pk_f16_f32 v174, v32, v33
	v_cvt_pk_f16_f32 v175, v34, v35
	global_store_dwordx2 v177, v[174:175], s[80:81] offset:96
	v_add_u32_e32 v177, 0x8000, v177
	v_add_u32_e32 v178, 0x8000, v178
	global_load_dwordx2 v[192:193], v178, s[80:81]
	global_load_dwordx2 v[194:195], v178, s[80:81] offset:32
	global_load_dwordx2 v[196:197], v178, s[80:81] offset:64
	global_load_dwordx2 v[198:199], v178, s[80:81] offset:96
	s_waitcnt vmcnt(11)
	v_cvt_f32_f16_e32 v164, v184
	v_cvt_f32_f16_sdwa v165, v184 dst_sel:DWORD dst_unused:UNUSED_PAD src0_sel:WORD_1
	v_cvt_f32_f16_e32 v166, v185
	v_cvt_f32_f16_sdwa v167, v185 dst_sel:DWORD dst_unused:UNUSED_PAD src0_sel:WORD_1
	v_pk_mul_f32 v[164:165], v[164:165], s[84:85] op_sel_hi:[1,0]
	v_pk_mul_f32 v[166:167], v[166:167], s[84:85] op_sel_hi:[1,0]
	v_pk_fma_f32 v[36:37], v[36:37], v[132:133], v[164:165]
	v_pk_fma_f32 v[38:39], v[38:39], v[134:135], v[166:167]
	v_cvt_pk_f16_f32 v172, v36, v37
	v_cvt_pk_f16_f32 v173, v38, v39
	global_store_dwordx2 v177, v[172:173], s[80:81]
	s_waitcnt vmcnt(11)
	v_cvt_f32_f16_e32 v164, v186
	v_cvt_f32_f16_sdwa v165, v186 dst_sel:DWORD dst_unused:UNUSED_PAD src0_sel:WORD_1
	v_cvt_f32_f16_e32 v166, v187
	v_cvt_f32_f16_sdwa v167, v187 dst_sel:DWORD dst_unused:UNUSED_PAD src0_sel:WORD_1
	v_pk_mul_f32 v[164:165], v[164:165], s[84:85] op_sel_hi:[1,0]
	v_pk_mul_f32 v[166:167], v[166:167], s[84:85] op_sel_hi:[1,0]
	v_pk_fma_f32 v[40:41], v[40:41], v[136:137], v[164:165]
	v_pk_fma_f32 v[42:43], v[42:43], v[138:139], v[166:167]
	v_cvt_pk_f16_f32 v174, v40, v41
	v_cvt_pk_f16_f32 v175, v42, v43
	global_store_dwordx2 v177, v[174:175], s[80:81] offset:32
	s_waitcnt vmcnt(11)
	v_cvt_f32_f16_e32 v164, v188
	v_cvt_f32_f16_sdwa v165, v188 dst_sel:DWORD dst_unused:UNUSED_PAD src0_sel:WORD_1
	v_cvt_f32_f16_e32 v166, v189
	v_cvt_f32_f16_sdwa v167, v189 dst_sel:DWORD dst_unused:UNUSED_PAD src0_sel:WORD_1
	v_pk_mul_f32 v[164:165], v[164:165], s[84:85] op_sel_hi:[1,0]
	v_pk_mul_f32 v[166:167], v[166:167], s[84:85] op_sel_hi:[1,0]
	v_pk_fma_f32 v[44:45], v[44:45], v[140:141], v[164:165]
	v_pk_fma_f32 v[46:47], v[46:47], v[142:143], v[166:167]
	v_cvt_pk_f16_f32 v172, v44, v45
	v_cvt_pk_f16_f32 v173, v46, v47
	global_store_dwordx2 v177, v[172:173], s[80:81] offset:64
	s_waitcnt vmcnt(11)
	v_cvt_f32_f16_e32 v164, v190
	v_cvt_f32_f16_sdwa v165, v190 dst_sel:DWORD dst_unused:UNUSED_PAD src0_sel:WORD_1
	v_cvt_f32_f16_e32 v166, v191
	v_cvt_f32_f16_sdwa v167, v191 dst_sel:DWORD dst_unused:UNUSED_PAD src0_sel:WORD_1
	v_pk_mul_f32 v[164:165], v[164:165], s[84:85] op_sel_hi:[1,0]
	v_pk_mul_f32 v[166:167], v[166:167], s[84:85] op_sel_hi:[1,0]
	v_pk_fma_f32 v[48:49], v[48:49], v[144:145], v[164:165]
	v_pk_fma_f32 v[50:51], v[50:51], v[146:147], v[166:167]
	v_cvt_pk_f16_f32 v174, v48, v49
	v_cvt_pk_f16_f32 v175, v50, v51
	global_store_dwordx2 v177, v[174:175], s[80:81] offset:96
	v_add_u32_e32 v177, 0x8000, v177
	s_waitcnt vmcnt(7)
	v_cvt_f32_f16_e32 v164, v192
	v_cvt_f32_f16_sdwa v165, v192 dst_sel:DWORD dst_unused:UNUSED_PAD src0_sel:WORD_1
	v_cvt_f32_f16_e32 v166, v193
	v_cvt_f32_f16_sdwa v167, v193 dst_sel:DWORD dst_unused:UNUSED_PAD src0_sel:WORD_1
	v_pk_mul_f32 v[164:165], v[164:165], s[84:85] op_sel_hi:[1,0]
	v_pk_mul_f32 v[166:167], v[166:167], s[84:85] op_sel_hi:[1,0]
	v_pk_fma_f32 v[52:53], v[52:53], v[132:133], v[164:165]
	v_pk_fma_f32 v[54:55], v[54:55], v[134:135], v[166:167]
	v_cvt_pk_f16_f32 v172, v52, v53
	v_cvt_pk_f16_f32 v173, v54, v55
	global_store_dwordx2 v177, v[172:173], s[80:81]
	s_waitcnt vmcnt(7)
	v_cvt_f32_f16_e32 v164, v194
	v_cvt_f32_f16_sdwa v165, v194 dst_sel:DWORD dst_unused:UNUSED_PAD src0_sel:WORD_1
	v_cvt_f32_f16_e32 v166, v195
	v_cvt_f32_f16_sdwa v167, v195 dst_sel:DWORD dst_unused:UNUSED_PAD src0_sel:WORD_1
	v_pk_mul_f32 v[164:165], v[164:165], s[84:85] op_sel_hi:[1,0]
	v_pk_mul_f32 v[166:167], v[166:167], s[84:85] op_sel_hi:[1,0]
	v_pk_fma_f32 v[56:57], v[56:57], v[136:137], v[164:165]
	v_pk_fma_f32 v[58:59], v[58:59], v[138:139], v[166:167]
	v_cvt_pk_f16_f32 v174, v56, v57
	v_cvt_pk_f16_f32 v175, v58, v59
	global_store_dwordx2 v177, v[174:175], s[80:81] offset:32
	s_waitcnt vmcnt(7)
	v_cvt_f32_f16_e32 v164, v196
	v_cvt_f32_f16_sdwa v165, v196 dst_sel:DWORD dst_unused:UNUSED_PAD src0_sel:WORD_1
	v_cvt_f32_f16_e32 v166, v197
	v_cvt_f32_f16_sdwa v167, v197 dst_sel:DWORD dst_unused:UNUSED_PAD src0_sel:WORD_1
	v_pk_mul_f32 v[164:165], v[164:165], s[84:85] op_sel_hi:[1,0]
	v_pk_mul_f32 v[166:167], v[166:167], s[84:85] op_sel_hi:[1,0]
	v_pk_fma_f32 v[60:61], v[60:61], v[140:141], v[164:165]
	v_pk_fma_f32 v[62:63], v[62:63], v[142:143], v[166:167]
	v_cvt_pk_f16_f32 v172, v60, v61
	v_cvt_pk_f16_f32 v173, v62, v63
	global_store_dwordx2 v177, v[172:173], s[80:81] offset:64
	s_waitcnt vmcnt(7)
	v_cvt_f32_f16_e32 v164, v198
	v_cvt_f32_f16_sdwa v165, v198 dst_sel:DWORD dst_unused:UNUSED_PAD src0_sel:WORD_1
	v_cvt_f32_f16_e32 v166, v199
	v_cvt_f32_f16_sdwa v167, v199 dst_sel:DWORD dst_unused:UNUSED_PAD src0_sel:WORD_1
	v_pk_mul_f32 v[164:165], v[164:165], s[84:85] op_sel_hi:[1,0]
	v_pk_mul_f32 v[166:167], v[166:167], s[84:85] op_sel_hi:[1,0]
	v_pk_fma_f32 v[64:65], v[64:65], v[144:145], v[164:165]
	v_pk_fma_f32 v[66:67], v[66:67], v[146:147], v[166:167]
	v_cvt_pk_f16_f32 v174, v64, v65
	v_cvt_pk_f16_f32 v175, v66, v67
	global_store_dwordx2 v177, v[174:175], s[80:81] offset:96
	s_nop 1
	s_add_i32 s24, s24, s64
	s_cmpk_gt_i32 s24, 0x27f
	s_cbranch_scc1 .LBB0_67
	s_branch .LBB0_51

.LBB0_164:
	s_lshr_b32 s55, s24, 3
	s_lshl_b32 s25, s55, 8
	s_lshl_b32 s55, s55, 3
	s_sub_i32 s55, s24, s55
	s_lshl_b32 s30, s55, 7
	s_lshl_b32 s55, s25, 11
	s_add_u32 s34, s50, s55
	s_addc_u32 s35, s51, 0
	s_lshl_b32 s55, s30, 11
	s_add_u32 s36, s48, s55
	s_addc_u32 s37, s49, 0
	v_readfirstlane_b32 s55, v200
	s_lshr_b32 s55, s55, 6
	s_lshl_b32 s31, s55, 11
	s_add_u32 s31, s31, 16
	s_lshl_b32 s32, s55, 10
	s_add_u32 s32, s32, 0x4010
	s_lshl_b32 s55, s55, 15
	s_add_u32 s36, s36, s55
	s_addc_u32 s37, s37, 0
	s_lshl_b32 s55, s55, 1
	s_add_u32 s34, s34, s55
	s_addc_u32 s35, s35, 0
	v_bfe_u32 v173, v200, 4, 2
	v_sub_u32_e32 v173, 0, v173
	v_and_b32_e32 v173, 3, v173
	v_and_b32_e32 v172, 3, v200
	v_xor_b32_e32 v172, v172, v173
	v_bfe_u32 v173, v200, 2, 4
	v_lshlrev_b32_e32 v173, 11, v173
	v_lshl_or_b32 v170, v172, 4, v173
	v_add_u32_e32 v171, 0x8000, v170
	v_bfe_u32 v172, v200, 2, 2
	v_sub_u32_e32 v172, 0, v172
	v_and_b32_e32 v172, 3, v172
	v_bfe_u32 v173, v200, 4, 2
	v_xor_b32_e32 v172, v172, v173
	v_and_b32_e32 v173, 15, v200
	v_bfe_u32 v174, v200, 7, 2
	v_lshl_or_b32 v174, v174, 6, v173
	v_lshlrev_b32_e32 v174, 6, v174
	v_lshl_or_b32 v164, v172, 4, v174
	v_bfe_u32 v174, v200, 6, 1
	v_lshl_or_b32 v174, v174, 6, v173
	v_lshlrev_b32_e32 v174, 6, v174
	v_lshl_or_b32 v165, v172, 4, v174
	v_add_u32_e32 v165, 0x4000, v165
	v_bfe_u32 v172, v200, 6, 1
	v_bfe_u32 v173, v200, 4, 2
	v_lshlrev_b32_e32 v172, 6, v172
	v_lshl_or_b32 v172, v173, 2, v172
	v_add_u32_e32 v172, s30, v172
	v_lshlrev_b32_e32 v172, 2, v172
	global_load_dwordx4 v[132:135], v172, s[42:43]
	global_load_dwordx4 v[136:139], v172, s[42:43] offset:64
	global_load_dwordx4 v[140:143], v172, s[42:43] offset:128
	global_load_dwordx4 v[144:147], v172, s[42:43] offset:192
	s_mov_b32 s53, 0x0
	s_add_u32 m0, s31, s53
	s_nop 0
	global_load_lds_dwordx4 v170, s[34:35]
	s_add_u32 m0, s31, s53
	s_add_u32 m0, m0, 0x400
	s_nop 0
	global_load_lds_dwordx4 v171, s[34:35]
	s_add_u32 m0, s32, s53
	s_nop 0
	global_load_lds_dwordx4 v170, s[36:37]
	s_add_u32 s34, s34, 64
	s_addc_u32 s35, s35, 0
	s_add_u32 s36, s36, 64
	s_addc_u32 s37, s37, 0
	s_mov_b32 s53, 0x6000
	s_add_u32 m0, s31, s53
	s_nop 0
	global_load_lds_dwordx4 v170, s[34:35]
	s_add_u32 m0, s31, s53
	s_add_u32 m0, m0, 0x400
	s_nop 0
	global_load_lds_dwordx4 v171, s[34:35]
	s_add_u32 m0, s32, s53
	s_nop 0
	global_load_lds_dwordx4 v170, s[36:37]
	s_add_u32 s34, s34, 64
	s_addc_u32 s35, s35, 0
	s_add_u32 s36, s36, 64
	s_addc_u32 s37, s37, 0
	s_mov_b32 s53, 0xc000
	s_add_u32 m0, s31, s53
	s_nop 0
	global_load_lds_dwordx4 v170, s[34:35]
	s_add_u32 m0, s31, s53
	s_add_u32 m0, m0, 0x400
	s_nop 0
	global_load_lds_dwordx4 v171, s[34:35]
	s_add_u32 m0, s32, s53
	s_nop 0
	global_load_lds_dwordx4 v170, s[36:37]
	s_add_u32 s34, s34, 64
	s_addc_u32 s35, s35, 0
	s_add_u32 s36, s36, 64
	s_addc_u32 s37, s37, 0
	s_mov_b32 s53, 0x12000
	s_add_u32 m0, s31, s53
	s_nop 0
	global_load_lds_dwordx4 v170, s[34:35]
	s_add_u32 m0, s31, s53
	s_add_u32 m0, m0, 0x400
	s_nop 0
	global_load_lds_dwordx4 v171, s[34:35]
	s_add_u32 m0, s32, s53
	s_nop 0
	global_load_lds_dwordx4 v170, s[36:37]
	s_add_u32 s34, s34, 64
	s_addc_u32 s35, s35, 0
	s_add_u32 s36, s36, 64
	s_addc_u32 s37, s37, 0
	s_waitcnt vmcnt(12)
	v_mov_b32_e32 v4, v132
	v_mov_b32_e32 v5, v133
	v_mov_b32_e32 v6, v134
	v_mov_b32_e32 v7, v135
	v_mov_b32_e32 v8, v136
	v_mov_b32_e32 v9, v137
	v_mov_b32_e32 v10, v138
	v_mov_b32_e32 v11, v139
	v_mov_b32_e32 v12, v140
	v_mov_b32_e32 v13, v141
	v_mov_b32_e32 v14, v142
	v_mov_b32_e32 v15, v143
	v_mov_b32_e32 v16, v144
	v_mov_b32_e32 v17, v145
	v_mov_b32_e32 v18, v146
	v_mov_b32_e32 v19, v147
	v_mov_b32_e32 v20, v132
	v_mov_b32_e32 v21, v133
	v_mov_b32_e32 v22, v134
	v_mov_b32_e32 v23, v135
	v_mov_b32_e32 v24, v136
	v_mov_b32_e32 v25, v137
	v_mov_b32_e32 v26, v138
	v_mov_b32_e32 v27, v139
	v_mov_b32_e32 v28, v140
	v_mov_b32_e32 v29, v141
	v_mov_b32_e32 v30, v142
	v_mov_b32_e32 v31, v143
	v_mov_b32_e32 v32, v144
	v_mov_b32_e32 v33, v145
	v_mov_b32_e32 v34, v146
	v_mov_b32_e32 v35, v147
	v_mov_b32_e32 v36, v132
	v_mov_b32_e32 v37, v133
	v_mov_b32_e32 v38, v134
	v_mov_b32_e32 v39, v135
	v_mov_b32_e32 v40, v136
	v_mov_b32_e32 v41, v137
	v_mov_b32_e32 v42, v138
	v_mov_b32_e32 v43, v139
	v_mov_b32_e32 v44, v140
	v_mov_b32_e32 v45, v141
	v_mov_b32_e32 v46, v142
	v_mov_b32_e32 v47, v143
	v_mov_b32_e32 v48, v144
	v_mov_b32_e32 v49, v145
	v_mov_b32_e32 v50, v146
	v_mov_b32_e32 v51, v147
	v_mov_b32_e32 v52, v132
	v_mov_b32_e32 v53, v133
	v_mov_b32_e32 v54, v134
	v_mov_b32_e32 v55, v135
	v_mov_b32_e32 v56, v136
	v_mov_b32_e32 v57, v137
	v_mov_b32_e32 v58, v138
	v_mov_b32_e32 v59, v139
	v_mov_b32_e32 v60, v140
	v_mov_b32_e32 v61, v141
	v_mov_b32_e32 v62, v142
	v_mov_b32_e32 v63, v143
	v_mov_b32_e32 v64, v144
	v_mov_b32_e32 v65, v145
	v_mov_b32_e32 v66, v146
	v_mov_b32_e32 v67, v147
	s_waitcnt vmcnt(9)
	s_barrier
	s_mov_b32 s52, 0
	s_mov_b32 s54, 0
	s_nop 1
	v_add_u32_e32 v168, s52, v165
	v_add_u32_e32 v169, s52, v164
	ds_read_b128 v[132:135], v168 offset:16
	ds_read_b128 v[136:139], v168 offset:1040
	ds_read_b128 v[140:143], v168 offset:2064
	ds_read_b128 v[144:147], v168 offset:3088
	ds_read_b128 v[184:187], v169 offset:16
	ds_read_b128 v[188:191], v169 offset:1040
	s_waitcnt lgkmcnt(0)
.Lt_out1n:
	v_add_u32_e32 v169, s52, v164
	v_mfma_f32_16x16x32_f16 v[4:7], v[132:135], v[184:187], v[4:7]
	ds_read_b128 v[192:195], v169 offset:2064
	v_mfma_f32_16x16x32_f16 v[8:11], v[136:139], v[184:187], v[8:11]
	ds_read_b128 v[196:199], v169 offset:3088
	v_mfma_f32_16x16x32_f16 v[12:15], v[140:143], v[184:187], v[12:15]
	v_mfma_f32_16x16x32_f16 v[16:19], v[144:147], v[184:187], v[16:19]
	v_mfma_f32_16x16x32_f16 v[20:23], v[132:135], v[188:191], v[20:23]
	v_mfma_f32_16x16x32_f16 v[24:27], v[136:139], v[188:191], v[24:27]
	v_mfma_f32_16x16x32_f16 v[28:31], v[140:143], v[188:191], v[28:31]
	v_mfma_f32_16x16x32_f16 v[32:35], v[144:147], v[188:191], v[32:35]
	s_waitcnt vmcnt(6) lgkmcnt(0)
	s_barrier
	s_add_i32 s53, s52, 0x6000
	s_cmp_lg_u32 s52, 0x12000
	s_cselect_b32 s53, s53, 0
	v_add_u32_e32 v168, s53, v165
	v_add_u32_e32 v169, s53, v164
	v_mfma_f32_16x16x32_f16 v[36:39], v[132:135], v[192:195], v[36:39]
	ds_read_b128 v[148:151], v168 offset:16
	ds_read_b128 v[184:187], v169 offset:16
	v_mfma_f32_16x16x32_f16 v[40:43], v[136:139], v[192:195], v[40:43]
	ds_read_b128 v[152:155], v168 offset:1040
	ds_read_b128 v[188:191], v169 offset:1040
	v_mfma_f32_16x16x32_f16 v[44:47], v[140:143], v[192:195], v[44:47]
	ds_read_b128 v[156:159], v168 offset:2064
	v_mfma_f32_16x16x32_f16 v[48:51], v[144:147], v[192:195], v[48:51]
	ds_read_b128 v[160:163], v168 offset:3088
	v_mfma_f32_16x16x32_f16 v[52:55], v[132:135], v[196:199], v[52:55]
	s_add_u32 m0, s31, s52
	s_nop 0
	global_load_lds_dwordx4 v170, s[34:35]
	v_mfma_f32_16x16x32_f16 v[56:59], v[136:139], v[196:199], v[56:59]
	s_add_u32 m0, s31, s52
	s_add_u32 m0, m0, 0x400
	s_nop 0
	global_load_lds_dwordx4 v171, s[34:35]
	v_mfma_f32_16x16x32_f16 v[60:63], v[140:143], v[196:199], v[60:63]
	s_add_u32 m0, s32, s52
	s_nop 0
	global_load_lds_dwordx4 v170, s[36:37]
	v_mfma_f32_16x16x32_f16 v[64:67], v[144:147], v[196:199], v[64:67]
	s_waitcnt lgkmcnt(0)
	s_mov_b32 s52, s53
	s_add_u32 s34, s34, 64
	s_addc_u32 s35, s35, 0
	s_add_u32 s36, s36, 64
	s_addc_u32 s37, s37, 0
	v_add_u32_e32 v169, s52, v164
	v_mfma_f32_16x16x32_f16 v[4:7], v[148:151], v[184:187], v[4:7]
	ds_read_b128 v[192:195], v169 offset:2064
	v_mfma_f32_16x16x32_f16 v[8:11], v[152:155], v[184:187], v[8:11]
	ds_read_b128 v[196:199], v169 offset:3088
	v_mfma_f32_16x16x32_f16 v[12:15], v[156:159], v[184:187], v[12:15]
	v_mfma_f32_16x16x32_f16 v[16:19], v[160:163], v[184:187], v[16:19]
	v_mfma_f32_16x16x32_f16 v[20:23], v[148:151], v[188:191], v[20:23]
	v_mfma_f32_16x16x32_f16 v[24:27], v[152:155], v[188:191], v[24:27]
	v_mfma_f32_16x16x32_f16 v[28:31], v[156:159], v[188:191], v[28:31]
	v_mfma_f32_16x16x32_f16 v[32:35], v[160:163], v[188:191], v[32:35]
	s_waitcnt vmcnt(6) lgkmcnt(0)
	s_barrier
	s_add_i32 s53, s52, 0x6000
	s_cmp_lg_u32 s52, 0x12000
	s_cselect_b32 s53, s53, 0
	v_add_u32_e32 v168, s53, v165
	v_add_u32_e32 v169, s53, v164
	v_mfma_f32_16x16x32_f16 v[36:39], v[148:151], v[192:195], v[36:39]
	ds_read_b128 v[132:135], v168 offset:16
	ds_read_b128 v[184:187], v169 offset:16
	v_mfma_f32_16x16x32_f16 v[40:43], v[152:155], v[192:195], v[40:43]
	ds_read_b128 v[136:139], v168 offset:1040
	ds_read_b128 v[188:191], v169 offset:1040
	v_mfma_f32_16x16x32_f16 v[44:47], v[156:159], v[192:195], v[44:47]
	ds_read_b128 v[140:143], v168 offset:2064
	v_mfma_f32_16x16x32_f16 v[48:51], v[160:163], v[192:195], v[48:51]
	ds_read_b128 v[144:147], v168 offset:3088
	v_mfma_f32_16x16x32_f16 v[52:55], v[148:151], v[196:199], v[52:55]
	s_add_u32 m0, s31, s52
	s_nop 0
	global_load_lds_dwordx4 v170, s[34:35]
	v_mfma_f32_16x16x32_f16 v[56:59], v[152:155], v[196:199], v[56:59]
	s_add_u32 m0, s31, s52
	s_add_u32 m0, m0, 0x400
	s_nop 0
	global_load_lds_dwordx4 v171, s[34:35]
	v_mfma_f32_16x16x32_f16 v[60:63], v[156:159], v[196:199], v[60:63]
	s_add_u32 m0, s32, s52
	s_nop 0
	global_load_lds_dwordx4 v170, s[36:37]
	v_mfma_f32_16x16x32_f16 v[64:67], v[160:163], v[196:199], v[64:67]
	s_waitcnt lgkmcnt(0)
	s_mov_b32 s52, s53
	s_add_u32 s34, s34, 64
	s_addc_u32 s35, s35, 0
	s_add_u32 s36, s36, 64
	s_addc_u32 s37, s37, 0
	s_add_i32 s54, s54, 2
	s_cmp_lt_u32 s54, 28
	s_cbranch_scc1 .Lt_out1n
	v_add_u32_e32 v169, s52, v164
	v_mfma_f32_16x16x32_f16 v[4:7], v[132:135], v[184:187], v[4:7]
	ds_read_b128 v[192:195], v169 offset:2064
	v_mfma_f32_16x16x32_f16 v[8:11], v[136:139], v[184:187], v[8:11]
	ds_read_b128 v[196:199], v169 offset:3088
	v_mfma_f32_16x16x32_f16 v[12:15], v[140:143], v[184:187], v[12:15]
	v_mfma_f32_16x16x32_f16 v[16:19], v[144:147], v[184:187], v[16:19]
	v_mfma_f32_16x16x32_f16 v[20:23], v[132:135], v[188:191], v[20:23]
	v_mfma_f32_16x16x32_f16 v[24:27], v[136:139], v[188:191], v[24:27]
	v_mfma_f32_16x16x32_f16 v[28:31], v[140:143], v[188:191], v[28:31]
	v_mfma_f32_16x16x32_f16 v[32:35], v[144:147], v[188:191], v[32:35]
	s_waitcnt vmcnt(6) lgkmcnt(0)
	s_barrier
	s_add_i32 s53, s52, 0x6000
	s_cmp_lg_u32 s52, 0x12000
	s_cselect_b32 s53, s53, 0
	v_add_u32_e32 v168, s53, v165
	v_add_u32_e32 v169, s53, v164
	v_mfma_f32_16x16x32_f16 v[36:39], v[132:135], v[192:195], v[36:39]
	ds_read_b128 v[148:151], v168 offset:16
	ds_read_b128 v[184:187], v169 offset:16
	v_mfma_f32_16x16x32_f16 v[40:43], v[136:139], v[192:195], v[40:43]
	ds_read_b128 v[152:155], v168 offset:1040
	ds_read_b128 v[188:191], v169 offset:1040
	v_mfma_f32_16x16x32_f16 v[44:47], v[140:143], v[192:195], v[44:47]
	ds_read_b128 v[156:159], v168 offset:2064
	v_mfma_f32_16x16x32_f16 v[48:51], v[144:147], v[192:195], v[48:51]
	ds_read_b128 v[160:163], v168 offset:3088
	v_mfma_f32_16x16x32_f16 v[52:55], v[132:135], v[196:199], v[52:55]
	v_mfma_f32_16x16x32_f16 v[56:59], v[136:139], v[196:199], v[56:59]
	v_mfma_f32_16x16x32_f16 v[60:63], v[140:143], v[196:199], v[60:63]
	v_mfma_f32_16x16x32_f16 v[64:67], v[144:147], v[196:199], v[64:67]
	s_waitcnt lgkmcnt(0)
	s_mov_b32 s52, s53
	v_add_u32_e32 v169, s52, v164
	v_mfma_f32_16x16x32_f16 v[4:7], v[148:151], v[184:187], v[4:7]
	ds_read_b128 v[192:195], v169 offset:2064
	v_mfma_f32_16x16x32_f16 v[8:11], v[152:155], v[184:187], v[8:11]
	ds_read_b128 v[196:199], v169 offset:3088
	v_mfma_f32_16x16x32_f16 v[12:15], v[156:159], v[184:187], v[12:15]
	v_mfma_f32_16x16x32_f16 v[16:19], v[160:163], v[184:187], v[16:19]
	v_mfma_f32_16x16x32_f16 v[20:23], v[148:151], v[188:191], v[20:23]
	v_mfma_f32_16x16x32_f16 v[24:27], v[152:155], v[188:191], v[24:27]
	v_mfma_f32_16x16x32_f16 v[28:31], v[156:159], v[188:191], v[28:31]
	v_mfma_f32_16x16x32_f16 v[32:35], v[160:163], v[188:191], v[32:35]
	s_waitcnt vmcnt(3) lgkmcnt(0)
	s_barrier
	s_add_i32 s53, s52, 0x6000
	s_cmp_lg_u32 s52, 0x12000
	s_cselect_b32 s53, s53, 0
	v_add_u32_e32 v168, s53, v165
	v_add_u32_e32 v169, s53, v164
	v_mfma_f32_16x16x32_f16 v[36:39], v[148:151], v[192:195], v[36:39]
	ds_read_b128 v[132:135], v168 offset:16
	ds_read_b128 v[184:187], v169 offset:16
	v_mfma_f32_16x16x32_f16 v[40:43], v[152:155], v[192:195], v[40:43]
	ds_read_b128 v[136:139], v168 offset:1040
	ds_read_b128 v[188:191], v169 offset:1040
	v_mfma_f32_16x16x32_f16 v[44:47], v[156:159], v[192:195], v[44:47]
	ds_read_b128 v[140:143], v168 offset:2064
	v_mfma_f32_16x16x32_f16 v[48:51], v[160:163], v[192:195], v[48:51]
	ds_read_b128 v[144:147], v168 offset:3088
	v_mfma_f32_16x16x32_f16 v[52:55], v[148:151], v[196:199], v[52:55]
	v_mfma_f32_16x16x32_f16 v[56:59], v[152:155], v[196:199], v[56:59]
	v_mfma_f32_16x16x32_f16 v[60:63], v[156:159], v[196:199], v[60:63]
	v_mfma_f32_16x16x32_f16 v[64:67], v[160:163], v[196:199], v[64:67]
	s_waitcnt lgkmcnt(0)
	s_mov_b32 s52, s53
	v_add_u32_e32 v169, s52, v164
	v_mfma_f32_16x16x32_f16 v[4:7], v[132:135], v[184:187], v[4:7]
	ds_read_b128 v[192:195], v169 offset:2064
	v_mfma_f32_16x16x32_f16 v[8:11], v[136:139], v[184:187], v[8:11]
	ds_read_b128 v[196:199], v169 offset:3088
	v_mfma_f32_16x16x32_f16 v[12:15], v[140:143], v[184:187], v[12:15]
	v_mfma_f32_16x16x32_f16 v[16:19], v[144:147], v[184:187], v[16:19]
	v_mfma_f32_16x16x32_f16 v[20:23], v[132:135], v[188:191], v[20:23]
	v_mfma_f32_16x16x32_f16 v[24:27], v[136:139], v[188:191], v[24:27]
	v_mfma_f32_16x16x32_f16 v[28:31], v[140:143], v[188:191], v[28:31]
	v_mfma_f32_16x16x32_f16 v[32:35], v[144:147], v[188:191], v[32:35]
	s_waitcnt vmcnt(0) lgkmcnt(0)
	s_barrier
	s_add_i32 s53, s52, 0x6000
	s_cmp_lg_u32 s52, 0x12000
	s_cselect_b32 s53, s53, 0
	v_add_u32_e32 v168, s53, v165
	v_add_u32_e32 v169, s53, v164
	v_mfma_f32_16x16x32_f16 v[36:39], v[132:135], v[192:195], v[36:39]
	ds_read_b128 v[148:151], v168 offset:16
	ds_read_b128 v[184:187], v169 offset:16
	v_mfma_f32_16x16x32_f16 v[40:43], v[136:139], v[192:195], v[40:43]
	ds_read_b128 v[152:155], v168 offset:1040
	ds_read_b128 v[188:191], v169 offset:1040
	v_mfma_f32_16x16x32_f16 v[44:47], v[140:143], v[192:195], v[44:47]
	ds_read_b128 v[156:159], v168 offset:2064
	v_mfma_f32_16x16x32_f16 v[48:51], v[144:147], v[192:195], v[48:51]
	ds_read_b128 v[160:163], v168 offset:3088
	v_mfma_f32_16x16x32_f16 v[52:55], v[132:135], v[196:199], v[52:55]
	v_mfma_f32_16x16x32_f16 v[56:59], v[136:139], v[196:199], v[56:59]
	v_mfma_f32_16x16x32_f16 v[60:63], v[140:143], v[196:199], v[60:63]
	v_mfma_f32_16x16x32_f16 v[64:67], v[144:147], v[196:199], v[64:67]
	s_waitcnt lgkmcnt(0)
	s_mov_b32 s52, s53
	v_add_u32_e32 v169, s52, v164
	v_mfma_f32_16x16x32_f16 v[4:7], v[148:151], v[184:187], v[4:7]
	ds_read_b128 v[192:195], v169 offset:2064
	v_mfma_f32_16x16x32_f16 v[8:11], v[152:155], v[184:187], v[8:11]
	ds_read_b128 v[196:199], v169 offset:3088
	v_mfma_f32_16x16x32_f16 v[12:15], v[156:159], v[184:187], v[12:15]
	v_mfma_f32_16x16x32_f16 v[16:19], v[160:163], v[184:187], v[16:19]
	v_mfma_f32_16x16x32_f16 v[20:23], v[148:151], v[188:191], v[20:23]
	v_mfma_f32_16x16x32_f16 v[24:27], v[152:155], v[188:191], v[24:27]
	v_mfma_f32_16x16x32_f16 v[28:31], v[156:159], v[188:191], v[28:31]
	v_mfma_f32_16x16x32_f16 v[32:35], v[160:163], v[188:191], v[32:35]
	s_waitcnt lgkmcnt(0)
	s_barrier
	v_mfma_f32_16x16x32_f16 v[36:39], v[148:151], v[192:195], v[36:39]
	v_mfma_f32_16x16x32_f16 v[40:43], v[152:155], v[192:195], v[40:43]
	v_mfma_f32_16x16x32_f16 v[44:47], v[156:159], v[192:195], v[44:47]
	v_mfma_f32_16x16x32_f16 v[48:51], v[160:163], v[192:195], v[48:51]
	v_mfma_f32_16x16x32_f16 v[52:55], v[148:151], v[196:199], v[52:55]
	v_mfma_f32_16x16x32_f16 v[56:59], v[152:155], v[196:199], v[56:59]
	v_mfma_f32_16x16x32_f16 v[60:63], v[156:159], v[196:199], v[60:63]
	v_mfma_f32_16x16x32_f16 v[64:67], v[160:163], v[196:199], v[64:67]
	s_sub_u32 s77, s25, 0x1000
	s_lshr_b32 s77, s77, 12
	s_add_u32 s77, s77, 1
	s_cmp_lt_u32 s25, 0x1000
	s_cselect_b32 s77, 0, s77
	s_mul_i32 s77, s77, 0x6000
	s_add_u32 s68, s28, s77
	s_addc_u32 s69, s29, 0
	s_add_u32 s68, s68, 0x20000
	s_addc_u32 s69, s69, 0
	s_lshl_b32 s82, s25, 11
	s_add_u32 s80, s46, s82
	s_addc_u32 s81, s47, 0
	s_lshl_b32 s82, s30, 1
	s_add_u32 s80, s80, s82
	s_addc_u32 s81, s81, 0
	v_and_b32_e32 v172, 15, v200
	v_bfe_u32 v173, v200, 4, 2
	v_bfe_u32 v174, v200, 6, 1
	v_bfe_u32 v175, v200, 7, 2
	v_lshlrev_b32_e32 v176, 6, v174
	v_lshl_or_b32 v176, v173, 2, v176
	v_lshl_or_b32 v175, v175, 6, v172
	v_lshlrev_b32_e32 v175, 11, v175
	v_lshl_add_u32 v177, v176, 1, v175
	v_add_u32_e32 v176, s30, v176
	v_lshlrev_b32_e32 v176, 2, v176
	global_load_dwordx4 v[132:135], v176, s[68:69]
	global_load_dwordx4 v[136:139], v176, s[68:69] offset:64
	global_load_dwordx4 v[140:143], v176, s[68:69] offset:128
	global_load_dwordx4 v[144:147], v176, s[68:69] offset:192
	v_mov_b32_e32 v178, v177
	global_load_dwordx2 v[184:185], v178, s[80:81]
	global_load_dwordx2 v[186:187], v178, s[80:81] offset:32
	global_load_dwordx2 v[188:189], v178, s[80:81] offset:64
	global_load_dwordx2 v[190:191], v178, s[80:81] offset:96
	v_add_u32_e32 v178, 0x8000, v178
	global_load_dwordx2 v[192:193], v178, s[80:81]
	global_load_dwordx2 v[194:195], v178, s[80:81] offset:32
	global_load_dwordx2 v[196:197], v178, s[80:81] offset:64
	global_load_dwordx2 v[198:199], v178, s[80:81] offset:96
	s_waitcnt vmcnt(7)
	v_cvt_f32_f16_e32 v164, v184
	v_cvt_f32_f16_sdwa v165, v184 dst_sel:DWORD dst_unused:UNUSED_PAD src0_sel:WORD_1
	v_cvt_f32_f16_e32 v166, v185
	v_cvt_f32_f16_sdwa v167, v185 dst_sel:DWORD dst_unused:UNUSED_PAD src0_sel:WORD_1
	v_pk_mul_f32 v[164:165], v[164:165], s[84:85] op_sel_hi:[1,0]
	v_pk_mul_f32 v[166:167], v[166:167], s[84:85] op_sel_hi:[1,0]
	v_pk_fma_f32 v[4:5], v[4:5], v[132:133], v[164:165]
	v_pk_fma_f32 v[6:7], v[6:7], v[134:135], v[166:167]
	v_cvt_pk_f16_f32 v172, v4, v5
	v_cvt_pk_f16_f32 v173, v6, v7
	global_store_dwordx2 v177, v[172:173], s[80:81]
	s_waitcnt vmcnt(7)
	v_cvt_f32_f16_e32 v164, v186
	v_cvt_f32_f16_sdwa v165, v186 dst_sel:DWORD dst_unused:UNUSED_PAD src0_sel:WORD_1
	v_cvt_f32_f16_e32 v166, v187
	v_cvt_f32_f16_sdwa v167, v187 dst_sel:DWORD dst_unused:UNUSED_PAD src0_sel:WORD_1
	v_pk_mul_f32 v[164:165], v[164:165], s[84:85] op_sel_hi:[1,0]
	v_pk_mul_f32 v[166:167], v[166:167], s[84:85] op_sel_hi:[1,0]
	v_pk_fma_f32 v[8:9], v[8:9], v[136:137], v[164:165]
	v_pk_fma_f32 v[10:11], v[10:11], v[138:139], v[166:167]
	v_cvt_pk_f16_f32 v174, v8, v9
	v_cvt_pk_f16_f32 v175, v10, v11
	global_store_dwordx2 v177, v[174:175], s[80:81] offset:32
	s_waitcnt vmcnt(7)
	v_cvt_f32_f16_e32 v164, v188
	v_cvt_f32_f16_sdwa v165, v188 dst_sel:DWORD dst_unused:UNUSED_PAD src0_sel:WORD_1
	v_cvt_f32_f16_e32 v166, v189
	v_cvt_f32_f16_sdwa v167, v189 dst_sel:DWORD dst_unused:UNUSED_PAD src0_sel:WORD_1
	v_pk_mul_f32 v[164:165], v[164:165], s[84:85] op_sel_hi:[1,0]
	v_pk_mul_f32 v[166:167], v[166:167], s[84:85] op_sel_hi:[1,0]
	v_pk_fma_f32 v[12:13], v[12:13], v[140:141], v[164:165]
	v_pk_fma_f32 v[14:15], v[14:15], v[142:143], v[166:167]
	v_cvt_pk_f16_f32 v172, v12, v13
	v_cvt_pk_f16_f32 v173, v14, v15
	global_store_dwordx2 v177, v[172:173], s[80:81] offset:64
	s_waitcnt vmcnt(7)
	v_cvt_f32_f16_e32 v164, v190
	v_cvt_f32_f16_sdwa v165, v190 dst_sel:DWORD dst_unused:UNUSED_PAD src0_sel:WORD_1
	v_cvt_f32_f16_e32 v166, v191
	v_cvt_f32_f16_sdwa v167, v191 dst_sel:DWORD dst_unused:UNUSED_PAD src0_sel:WORD_1
	v_pk_mul_f32 v[164:165], v[164:165], s[84:85] op_sel_hi:[1,0]
	v_pk_mul_f32 v[166:167], v[166:167], s[84:85] op_sel_hi:[1,0]
	v_pk_fma_f32 v[16:17], v[16:17], v[144:145], v[164:165]
	v_pk_fma_f32 v[18:19], v[18:19], v[146:147], v[166:167]
	v_cvt_pk_f16_f32 v174, v16, v17
	v_cvt_pk_f16_f32 v175, v18, v19
	global_store_dwordx2 v177, v[174:175], s[80:81] offset:96
	v_add_u32_e32 v177, 0x8000, v177
	v_add_u32_e32 v178, 0x8000, v178
	global_load_dwordx2 v[184:185], v178, s[80:81]
	global_load_dwordx2 v[186:187], v178, s[80:81] offset:32
	global_load_dwordx2 v[188:189], v178, s[80:81] offset:64
	global_load_dwordx2 v[190:191], v178, s[80:81] offset:96
	s_waitcnt vmcnt(11)
	v_cvt_f32_f16_e32 v164, v192
	v_cvt_f32_f16_sdwa v165, v192 dst_sel:DWORD dst_unused:UNUSED_PAD src0_sel:WORD_1
	v_cvt_f32_f16_e32 v166, v193
	v_cvt_f32_f16_sdwa v167, v193 dst_sel:DWORD dst_unused:UNUSED_PAD src0_sel:WORD_1
	v_pk_mul_f32 v[164:165], v[164:165], s[84:85] op_sel_hi:[1,0]
	v_pk_mul_f32 v[166:167], v[166:167], s[84:85] op_sel_hi:[1,0]
	v_pk_fma_f32 v[20:21], v[20:21], v[132:133], v[164:165]
	v_pk_fma_f32 v[22:23], v[22:23], v[134:135], v[166:167]
	v_cvt_pk_f16_f32 v172, v20, v21
	v_cvt_pk_f16_f32 v173, v22, v23
	global_store_dwordx2 v177, v[172:173], s[80:81]
	s_waitcnt vmcnt(11)
	v_cvt_f32_f16_e32 v164, v194
	v_cvt_f32_f16_sdwa v165, v194 dst_sel:DWORD dst_unused:UNUSED_PAD src0_sel:WORD_1
	v_cvt_f32_f16_e32 v166, v195
	v_cvt_f32_f16_sdwa v167, v195 dst_sel:DWORD dst_unused:UNUSED_PAD src0_sel:WORD_1
	v_pk_mul_f32 v[164:165], v[164:165], s[84:85] op_sel_hi:[1,0]
	v_pk_mul_f32 v[166:167], v[166:167], s[84:85] op_sel_hi:[1,0]
	v_pk_fma_f32 v[24:25], v[24:25], v[136:137], v[164:165]
	v_pk_fma_f32 v[26:27], v[26:27], v[138:139], v[166:167]
	v_cvt_pk_f16_f32 v174, v24, v25
	v_cvt_pk_f16_f32 v175, v26, v27
	global_store_dwordx2 v177, v[174:175], s[80:81] offset:32
	s_waitcnt vmcnt(11)
	v_cvt_f32_f16_e32 v164, v196
	v_cvt_f32_f16_sdwa v165, v196 dst_sel:DWORD dst_unused:UNUSED_PAD src0_sel:WORD_1
	v_cvt_f32_f16_e32 v166, v197
	v_cvt_f32_f16_sdwa v167, v197 dst_sel:DWORD dst_unused:UNUSED_PAD src0_sel:WORD_1
	v_pk_mul_f32 v[164:165], v[164:165], s[84:85] op_sel_hi:[1,0]
	v_pk_mul_f32 v[166:167], v[166:167], s[84:85] op_sel_hi:[1,0]
	v_pk_fma_f32 v[28:29], v[28:29], v[140:141], v[164:165]
	v_pk_fma_f32 v[30:31], v[30:31], v[142:143], v[166:167]
	v_cvt_pk_f16_f32 v172, v28, v29
	v_cvt_pk_f16_f32 v173, v30, v31
	global_store_dwordx2 v177, v[172:173], s[80:81] offset:64
	s_waitcnt vmcnt(11)
	v_cvt_f32_f16_e32 v164, v198
	v_cvt_f32_f16_sdwa v165, v198 dst_sel:DWORD dst_unused:UNUSED_PAD src0_sel:WORD_1
	v_cvt_f32_f16_e32 v166, v199
	v_cvt_f32_f16_sdwa v167, v199 dst_sel:DWORD dst_unused:UNUSED_PAD src0_sel:WORD_1
	v_pk_mul_f32 v[164:165], v[164:165], s[84:85] op_sel_hi:[1,0]
	v_pk_mul_f32 v[166:167], v[166:167], s[84:85] op_sel_hi:[1,0]
	v_pk_fma_f32 v[32:33], v[32:33], v[144:145], v[164:165]
	v_pk_fma_f32 v[34:35], v[34:35], v[146:147], v[166:167]
	v_cvt_pk_f16_f32 v174, v32, v33
	v_cvt_pk_f16_f32 v175, v34, v35
	global_store_dwordx2 v177, v[174:175], s[80:81] offset:96
	v_add_u32_e32 v177, 0x8000, v177
	v_add_u32_e32 v178, 0x8000, v178
	global_load_dwordx2 v[192:193], v178, s[80:81]
	global_load_dwordx2 v[194:195], v178, s[80:81] offset:32
	global_load_dwordx2 v[196:197], v178, s[80:81] offset:64
	global_load_dwordx2 v[198:199], v178, s[80:81] offset:96
	s_waitcnt vmcnt(11)
	v_cvt_f32_f16_e32 v164, v184
	v_cvt_f32_f16_sdwa v165, v184 dst_sel:DWORD dst_unused:UNUSED_PAD src0_sel:WORD_1
	v_cvt_f32_f16_e32 v166, v185
	v_cvt_f32_f16_sdwa v167, v185 dst_sel:DWORD dst_unused:UNUSED_PAD src0_sel:WORD_1
	v_pk_mul_f32 v[164:165], v[164:165], s[84:85] op_sel_hi:[1,0]
	v_pk_mul_f32 v[166:167], v[166:167], s[84:85] op_sel_hi:[1,0]
	v_pk_fma_f32 v[36:37], v[36:37], v[132:133], v[164:165]
	v_pk_fma_f32 v[38:39], v[38:39], v[134:135], v[166:167]
	v_cvt_pk_f16_f32 v172, v36, v37
	v_cvt_pk_f16_f32 v173, v38, v39
	global_store_dwordx2 v177, v[172:173], s[80:81]
	s_waitcnt vmcnt(11)
	v_cvt_f32_f16_e32 v164, v186
	v_cvt_f32_f16_sdwa v165, v186 dst_sel:DWORD dst_unused:UNUSED_PAD src0_sel:WORD_1
	v_cvt_f32_f16_e32 v166, v187
	v_cvt_f32_f16_sdwa v167, v187 dst_sel:DWORD dst_unused:UNUSED_PAD src0_sel:WORD_1
	v_pk_mul_f32 v[164:165], v[164:165], s[84:85] op_sel_hi:[1,0]
	v_pk_mul_f32 v[166:167], v[166:167], s[84:85] op_sel_hi:[1,0]
	v_pk_fma_f32 v[40:41], v[40:41], v[136:137], v[164:165]
	v_pk_fma_f32 v[42:43], v[42:43], v[138:139], v[166:167]
	v_cvt_pk_f16_f32 v174, v40, v41
	v_cvt_pk_f16_f32 v175, v42, v43
	global_store_dwordx2 v177, v[174:175], s[80:81] offset:32
	s_waitcnt vmcnt(11)
	v_cvt_f32_f16_e32 v164, v188
	v_cvt_f32_f16_sdwa v165, v188 dst_sel:DWORD dst_unused:UNUSED_PAD src0_sel:WORD_1
	v_cvt_f32_f16_e32 v166, v189
	v_cvt_f32_f16_sdwa v167, v189 dst_sel:DWORD dst_unused:UNUSED_PAD src0_sel:WORD_1
	v_pk_mul_f32 v[164:165], v[164:165], s[84:85] op_sel_hi:[1,0]
	v_pk_mul_f32 v[166:167], v[166:167], s[84:85] op_sel_hi:[1,0]
	v_pk_fma_f32 v[44:45], v[44:45], v[140:141], v[164:165]
	v_pk_fma_f32 v[46:47], v[46:47], v[142:143], v[166:167]
	v_cvt_pk_f16_f32 v172, v44, v45
	v_cvt_pk_f16_f32 v173, v46, v47
	global_store_dwordx2 v177, v[172:173], s[80:81] offset:64
	s_waitcnt vmcnt(11)
	v_cvt_f32_f16_e32 v164, v190
	v_cvt_f32_f16_sdwa v165, v190 dst_sel:DWORD dst_unused:UNUSED_PAD src0_sel:WORD_1
	v_cvt_f32_f16_e32 v166, v191
	v_cvt_f32_f16_sdwa v167, v191 dst_sel:DWORD dst_unused:UNUSED_PAD src0_sel:WORD_1
	v_pk_mul_f32 v[164:165], v[164:165], s[84:85] op_sel_hi:[1,0]
	v_pk_mul_f32 v[166:167], v[166:167], s[84:85] op_sel_hi:[1,0]
	v_pk_fma_f32 v[48:49], v[48:49], v[144:145], v[164:165]
	v_pk_fma_f32 v[50:51], v[50:51], v[146:147], v[166:167]
	v_cvt_pk_f16_f32 v174, v48, v49
	v_cvt_pk_f16_f32 v175, v50, v51
	global_store_dwordx2 v177, v[174:175], s[80:81] offset:96
	v_add_u32_e32 v177, 0x8000, v177
	s_waitcnt vmcnt(7)
	v_cvt_f32_f16_e32 v164, v192
	v_cvt_f32_f16_sdwa v165, v192 dst_sel:DWORD dst_unused:UNUSED_PAD src0_sel:WORD_1
	v_cvt_f32_f16_e32 v166, v193
	v_cvt_f32_f16_sdwa v167, v193 dst_sel:DWORD dst_unused:UNUSED_PAD src0_sel:WORD_1
	v_pk_mul_f32 v[164:165], v[164:165], s[84:85] op_sel_hi:[1,0]
	v_pk_mul_f32 v[166:167], v[166:167], s[84:85] op_sel_hi:[1,0]
	v_pk_fma_f32 v[52:53], v[52:53], v[132:133], v[164:165]
	v_pk_fma_f32 v[54:55], v[54:55], v[134:135], v[166:167]
	v_cvt_pk_f16_f32 v172, v52, v53
	v_cvt_pk_f16_f32 v173, v54, v55
	global_store_dwordx2 v177, v[172:173], s[80:81]
	s_waitcnt vmcnt(7)
	v_cvt_f32_f16_e32 v164, v194
	v_cvt_f32_f16_sdwa v165, v194 dst_sel:DWORD dst_unused:UNUSED_PAD src0_sel:WORD_1
	v_cvt_f32_f16_e32 v166, v195
	v_cvt_f32_f16_sdwa v167, v195 dst_sel:DWORD dst_unused:UNUSED_PAD src0_sel:WORD_1
	v_pk_mul_f32 v[164:165], v[164:165], s[84:85] op_sel_hi:[1,0]
	v_pk_mul_f32 v[166:167], v[166:167], s[84:85] op_sel_hi:[1,0]
	v_pk_fma_f32 v[56:57], v[56:57], v[136:137], v[164:165]
	v_pk_fma_f32 v[58:59], v[58:59], v[138:139], v[166:167]
	v_cvt_pk_f16_f32 v174, v56, v57
	v_cvt_pk_f16_f32 v175, v58, v59
	global_store_dwordx2 v177, v[174:175], s[80:81] offset:32
	s_waitcnt vmcnt(7)
	v_cvt_f32_f16_e32 v164, v196
	v_cvt_f32_f16_sdwa v165, v196 dst_sel:DWORD dst_unused:UNUSED_PAD src0_sel:WORD_1
	v_cvt_f32_f16_e32 v166, v197
	v_cvt_f32_f16_sdwa v167, v197 dst_sel:DWORD dst_unused:UNUSED_PAD src0_sel:WORD_1
	v_pk_mul_f32 v[164:165], v[164:165], s[84:85] op_sel_hi:[1,0]
	v_pk_mul_f32 v[166:167], v[166:167], s[84:85] op_sel_hi:[1,0]
	v_pk_fma_f32 v[60:61], v[60:61], v[140:141], v[164:165]
	v_pk_fma_f32 v[62:63], v[62:63], v[142:143], v[166:167]
	v_cvt_pk_f16_f32 v172, v60, v61
	v_cvt_pk_f16_f32 v173, v62, v63
	global_store_dwordx2 v177, v[172:173], s[80:81] offset:64
	s_waitcnt vmcnt(7)
	v_cvt_f32_f16_e32 v164, v198
	v_cvt_f32_f16_sdwa v165, v198 dst_sel:DWORD dst_unused:UNUSED_PAD src0_sel:WORD_1
	v_cvt_f32_f16_e32 v166, v199
	v_cvt_f32_f16_sdwa v167, v199 dst_sel:DWORD dst_unused:UNUSED_PAD src0_sel:WORD_1
	v_pk_mul_f32 v[164:165], v[164:165], s[84:85] op_sel_hi:[1,0]
	v_pk_mul_f32 v[166:167], v[166:167], s[84:85] op_sel_hi:[1,0]
	v_pk_fma_f32 v[64:65], v[64:65], v[144:145], v[164:165]
	v_pk_fma_f32 v[66:67], v[66:67], v[146:147], v[166:167]
	v_cvt_pk_f16_f32 v174, v64, v65
	v_cvt_pk_f16_f32 v175, v66, v67
	global_store_dwordx2 v177, v[174:175], s[80:81] offset:96
	s_nop 1
	s_add_i32 s24, s24, s64
	s_cmpk_gt_i32 s24, 0x27f
	s_cbranch_scc1 .LBB0_177
	s_branch .LBB0_164

.LBB0_704:
	s_waitcnt lgkmcnt(0)
	s_lshl_b64 s[50:51], s[30:31], 13
	s_add_u32 s50, s50, s36
	s_addc_u32 s51, s51, s37
	s_lshl_b32 vcc_hi, s52, 3
	s_sub_i32 vcc_hi, s24, vcc_hi
	s_lshl_b32 s30, vcc_hi, 7
	s_lshl_b32 vcc_hi, s30, 13
	s_add_u32 s54, s48, vcc_hi
	s_addc_u32 s55, s49, 0
	v_readfirstlane_b32 vcc_hi, v200
	s_lshr_b32 vcc_hi, vcc_hi, 6
	s_lshl_b32 s25, vcc_hi, 11
	s_add_u32 s25, s25, 16
	s_lshl_b32 s32, vcc_hi, 10
	s_add_u32 s32, s32, 0x4010
	s_lshl_b32 vcc_hi, vcc_hi, 17
	s_add_u32 s54, s54, vcc_hi
	s_addc_u32 s55, s55, 0
	s_lshl_b32 vcc_hi, vcc_hi, 1
	s_add_u32 s50, s50, vcc_hi
	s_addc_u32 s51, s51, 0
	v_bfe_u32 v173, v200, 4, 2
	v_sub_u32_e32 v173, 0, v173
	v_and_b32_e32 v173, 3, v173
	v_and_b32_e32 v172, 3, v200
	v_xor_b32_e32 v172, v172, v173
	v_bfe_u32 v173, v200, 2, 4
	v_lshlrev_b32_e32 v173, 13, v173
	v_lshl_or_b32 v170, v172, 4, v173
	v_add_u32_e32 v171, 0x20000, v170
	v_bfe_u32 v172, v200, 2, 2
	v_sub_u32_e32 v172, 0, v172
	v_and_b32_e32 v172, 3, v172
	v_bfe_u32 v173, v200, 4, 2
	v_xor_b32_e32 v172, v172, v173
	v_and_b32_e32 v173, 15, v200
	v_bfe_u32 v174, v200, 7, 2
	v_lshl_or_b32 v174, v174, 6, v173
	v_lshlrev_b32_e32 v174, 6, v174
	v_lshl_or_b32 v164, v172, 4, v174
	v_bfe_u32 v174, v200, 6, 1
	v_lshl_or_b32 v174, v174, 6, v173
	v_lshlrev_b32_e32 v174, 6, v174
	v_lshl_or_b32 v165, v172, 4, v174
	v_add_u32_e32 v165, 0x4000, v165
	v_bfe_u32 v172, v200, 6, 1
	v_bfe_u32 v173, v200, 4, 2
	v_lshlrev_b32_e32 v172, 6, v172
	v_lshl_or_b32 v172, v173, 2, v172
	v_add_u32_e32 v172, s30, v172
	v_lshlrev_b32_e32 v172, 2, v172
	global_load_dwordx4 v[132:135], v172, s[42:43]
	global_load_dwordx4 v[136:139], v172, s[42:43] offset:64
	global_load_dwordx4 v[140:143], v172, s[42:43] offset:128
	global_load_dwordx4 v[144:147], v172, s[42:43] offset:192
	s_mov_b32 s53, 0x0
	s_add_u32 m0, s25, s53
	s_nop 0
	global_load_lds_dwordx4 v170, s[50:51]
	s_add_u32 m0, s25, s53
	s_add_u32 m0, m0, 0x400
	s_nop 0
	global_load_lds_dwordx4 v171, s[50:51]
	s_add_u32 m0, s32, s53
	s_nop 0
	global_load_lds_dwordx4 v170, s[54:55]
	s_add_u32 s50, s50, 64
	s_addc_u32 s51, s51, 0
	s_add_u32 s54, s54, 64
	s_addc_u32 s55, s55, 0
	s_mov_b32 s53, 0x6000
	s_add_u32 m0, s25, s53
	s_nop 0
	global_load_lds_dwordx4 v170, s[50:51]
	s_add_u32 m0, s25, s53
	s_add_u32 m0, m0, 0x400
	s_nop 0
	global_load_lds_dwordx4 v171, s[50:51]
	s_add_u32 m0, s32, s53
	s_nop 0
	global_load_lds_dwordx4 v170, s[54:55]
	s_add_u32 s50, s50, 64
	s_addc_u32 s51, s51, 0
	s_add_u32 s54, s54, 64
	s_addc_u32 s55, s55, 0
	s_mov_b32 s53, 0xc000
	s_add_u32 m0, s25, s53
	s_nop 0
	global_load_lds_dwordx4 v170, s[50:51]
	s_add_u32 m0, s25, s53
	s_add_u32 m0, m0, 0x400
	s_nop 0
	global_load_lds_dwordx4 v171, s[50:51]
	s_add_u32 m0, s32, s53
	s_nop 0
	global_load_lds_dwordx4 v170, s[54:55]
	s_add_u32 s50, s50, 64
	s_addc_u32 s51, s51, 0
	s_add_u32 s54, s54, 64
	s_addc_u32 s55, s55, 0
	s_mov_b32 s53, 0x12000
	s_add_u32 m0, s25, s53
	s_nop 0
	global_load_lds_dwordx4 v170, s[50:51]
	s_add_u32 m0, s25, s53
	s_add_u32 m0, m0, 0x400
	s_nop 0
	global_load_lds_dwordx4 v171, s[50:51]
	s_add_u32 m0, s32, s53
	s_nop 0
	global_load_lds_dwordx4 v170, s[54:55]
	s_add_u32 s50, s50, 64
	s_addc_u32 s51, s51, 0
	s_add_u32 s54, s54, 64
	s_addc_u32 s55, s55, 0
	s_waitcnt vmcnt(12)
	v_mov_b32_e32 v4, v132
	v_mov_b32_e32 v5, v133
	v_mov_b32_e32 v6, v134
	v_mov_b32_e32 v7, v135
	v_mov_b32_e32 v8, v136
	v_mov_b32_e32 v9, v137
	v_mov_b32_e32 v10, v138
	v_mov_b32_e32 v11, v139
	v_mov_b32_e32 v12, v140
	v_mov_b32_e32 v13, v141
	v_mov_b32_e32 v14, v142
	v_mov_b32_e32 v15, v143
	v_mov_b32_e32 v16, v144
	v_mov_b32_e32 v17, v145
	v_mov_b32_e32 v18, v146
	v_mov_b32_e32 v19, v147
	v_mov_b32_e32 v20, v132
	v_mov_b32_e32 v21, v133
	v_mov_b32_e32 v22, v134
	v_mov_b32_e32 v23, v135
	v_mov_b32_e32 v24, v136
	v_mov_b32_e32 v25, v137
	v_mov_b32_e32 v26, v138
	v_mov_b32_e32 v27, v139
	v_mov_b32_e32 v28, v140
	v_mov_b32_e32 v29, v141
	v_mov_b32_e32 v30, v142
	v_mov_b32_e32 v31, v143
	v_mov_b32_e32 v32, v144
	v_mov_b32_e32 v33, v145
	v_mov_b32_e32 v34, v146
	v_mov_b32_e32 v35, v147
	v_mov_b32_e32 v36, v132
	v_mov_b32_e32 v37, v133
	v_mov_b32_e32 v38, v134
	v_mov_b32_e32 v39, v135
	v_mov_b32_e32 v40, v136
	v_mov_b32_e32 v41, v137
	v_mov_b32_e32 v42, v138
	v_mov_b32_e32 v43, v139
	v_mov_b32_e32 v44, v140
	v_mov_b32_e32 v45, v141
	v_mov_b32_e32 v46, v142
	v_mov_b32_e32 v47, v143
	v_mov_b32_e32 v48, v144
	v_mov_b32_e32 v49, v145
	v_mov_b32_e32 v50, v146
	v_mov_b32_e32 v51, v147
	v_mov_b32_e32 v52, v132
	v_mov_b32_e32 v53, v133
	v_mov_b32_e32 v54, v134
	v_mov_b32_e32 v55, v135
	v_mov_b32_e32 v56, v136
	v_mov_b32_e32 v57, v137
	v_mov_b32_e32 v58, v138
	v_mov_b32_e32 v59, v139
	v_mov_b32_e32 v60, v140
	v_mov_b32_e32 v61, v141
	v_mov_b32_e32 v62, v142
	v_mov_b32_e32 v63, v143
	v_mov_b32_e32 v64, v144
	v_mov_b32_e32 v65, v145
	v_mov_b32_e32 v66, v146
	v_mov_b32_e32 v67, v147
	s_waitcnt vmcnt(9)
	s_barrier
	s_mov_b32 s35, 0
	s_mov_b32 s65, 0
	s_nop 1
	v_add_u32_e32 v168, s35, v165
	v_add_u32_e32 v169, s35, v164
	ds_read_b128 v[132:135], v168 offset:16
	ds_read_b128 v[136:139], v168 offset:1040
	ds_read_b128 v[140:143], v168 offset:2064
	ds_read_b128 v[144:147], v168 offset:3088
	ds_read_b128 v[184:187], v169 offset:16
	ds_read_b128 v[188:191], v169 offset:1040
	s_waitcnt lgkmcnt(0)
.Lt_mlp2an:
	v_add_u32_e32 v169, s35, v164
	v_mfma_f32_16x16x32_f16 v[4:7], v[132:135], v[184:187], v[4:7]
	ds_read_b128 v[192:195], v169 offset:2064
	v_mfma_f32_16x16x32_f16 v[8:11], v[136:139], v[184:187], v[8:11]
	ds_read_b128 v[196:199], v169 offset:3088
	v_mfma_f32_16x16x32_f16 v[12:15], v[140:143], v[184:187], v[12:15]
	v_mfma_f32_16x16x32_f16 v[16:19], v[144:147], v[184:187], v[16:19]
	v_mfma_f32_16x16x32_f16 v[20:23], v[132:135], v[188:191], v[20:23]
	v_mfma_f32_16x16x32_f16 v[24:27], v[136:139], v[188:191], v[24:27]
	v_mfma_f32_16x16x32_f16 v[28:31], v[140:143], v[188:191], v[28:31]
	v_mfma_f32_16x16x32_f16 v[32:35], v[144:147], v[188:191], v[32:35]
	s_waitcnt vmcnt(6) lgkmcnt(0)
	s_barrier
	s_add_i32 s53, s35, 0x6000
	s_cmp_lg_u32 s35, 0x12000
	s_cselect_b32 s53, s53, 0
	v_add_u32_e32 v168, s53, v165
	v_add_u32_e32 v169, s53, v164
	v_mfma_f32_16x16x32_f16 v[36:39], v[132:135], v[192:195], v[36:39]
	ds_read_b128 v[148:151], v168 offset:16
	ds_read_b128 v[184:187], v169 offset:16
	v_mfma_f32_16x16x32_f16 v[40:43], v[136:139], v[192:195], v[40:43]
	ds_read_b128 v[152:155], v168 offset:1040
	ds_read_b128 v[188:191], v169 offset:1040
	v_mfma_f32_16x16x32_f16 v[44:47], v[140:143], v[192:195], v[44:47]
	ds_read_b128 v[156:159], v168 offset:2064
	v_mfma_f32_16x16x32_f16 v[48:51], v[144:147], v[192:195], v[48:51]
	ds_read_b128 v[160:163], v168 offset:3088
	v_mfma_f32_16x16x32_f16 v[52:55], v[132:135], v[196:199], v[52:55]
	s_add_u32 m0, s25, s35
	s_nop 0
	global_load_lds_dwordx4 v170, s[50:51]
	v_mfma_f32_16x16x32_f16 v[56:59], v[136:139], v[196:199], v[56:59]
	s_add_u32 m0, s25, s35
	s_add_u32 m0, m0, 0x400
	s_nop 0
	global_load_lds_dwordx4 v171, s[50:51]
	v_mfma_f32_16x16x32_f16 v[60:63], v[140:143], v[196:199], v[60:63]
	s_add_u32 m0, s32, s35
	s_nop 0
	global_load_lds_dwordx4 v170, s[54:55]
	v_mfma_f32_16x16x32_f16 v[64:67], v[144:147], v[196:199], v[64:67]
	s_waitcnt lgkmcnt(0)
	s_mov_b32 s35, s53
	s_add_u32 s50, s50, 64
	s_addc_u32 s51, s51, 0
	s_add_u32 s54, s54, 64
	s_addc_u32 s55, s55, 0
	v_add_u32_e32 v169, s35, v164
	v_mfma_f32_16x16x32_f16 v[4:7], v[148:151], v[184:187], v[4:7]
	ds_read_b128 v[192:195], v169 offset:2064
	v_mfma_f32_16x16x32_f16 v[8:11], v[152:155], v[184:187], v[8:11]
	ds_read_b128 v[196:199], v169 offset:3088
	v_mfma_f32_16x16x32_f16 v[12:15], v[156:159], v[184:187], v[12:15]
	v_mfma_f32_16x16x32_f16 v[16:19], v[160:163], v[184:187], v[16:19]
	v_mfma_f32_16x16x32_f16 v[20:23], v[148:151], v[188:191], v[20:23]
	v_mfma_f32_16x16x32_f16 v[24:27], v[152:155], v[188:191], v[24:27]
	v_mfma_f32_16x16x32_f16 v[28:31], v[156:159], v[188:191], v[28:31]
	v_mfma_f32_16x16x32_f16 v[32:35], v[160:163], v[188:191], v[32:35]
	s_waitcnt vmcnt(6) lgkmcnt(0)
	s_barrier
	s_add_i32 s53, s35, 0x6000
	s_cmp_lg_u32 s35, 0x12000
	s_cselect_b32 s53, s53, 0
	v_add_u32_e32 v168, s53, v165
	v_add_u32_e32 v169, s53, v164
	v_mfma_f32_16x16x32_f16 v[36:39], v[148:151], v[192:195], v[36:39]
	ds_read_b128 v[132:135], v168 offset:16
	ds_read_b128 v[184:187], v169 offset:16
	v_mfma_f32_16x16x32_f16 v[40:43], v[152:155], v[192:195], v[40:43]
	ds_read_b128 v[136:139], v168 offset:1040
	ds_read_b128 v[188:191], v169 offset:1040
	v_mfma_f32_16x16x32_f16 v[44:47], v[156:159], v[192:195], v[44:47]
	ds_read_b128 v[140:143], v168 offset:2064
	v_mfma_f32_16x16x32_f16 v[48:51], v[160:163], v[192:195], v[48:51]
	ds_read_b128 v[144:147], v168 offset:3088
	v_mfma_f32_16x16x32_f16 v[52:55], v[148:151], v[196:199], v[52:55]
	s_add_u32 m0, s25, s35
	s_nop 0
	global_load_lds_dwordx4 v170, s[50:51]
	v_mfma_f32_16x16x32_f16 v[56:59], v[152:155], v[196:199], v[56:59]
	s_add_u32 m0, s25, s35
	s_add_u32 m0, m0, 0x400
	s_nop 0
	global_load_lds_dwordx4 v171, s[50:51]
	v_mfma_f32_16x16x32_f16 v[60:63], v[156:159], v[196:199], v[60:63]
	s_add_u32 m0, s32, s35
	s_nop 0
	global_load_lds_dwordx4 v170, s[54:55]
	v_mfma_f32_16x16x32_f16 v[64:67], v[160:163], v[196:199], v[64:67]
	s_waitcnt lgkmcnt(0)
	s_mov_b32 s35, s53
	s_add_u32 s50, s50, 64
	s_addc_u32 s51, s51, 0
	s_add_u32 s54, s54, 64
	s_addc_u32 s55, s55, 0
	s_add_i32 s65, s65, 2
	s_cmp_lt_u32 s65, 124
	s_cbranch_scc1 .Lt_mlp2an
	v_add_u32_e32 v169, s35, v164
	v_mfma_f32_16x16x32_f16 v[4:7], v[132:135], v[184:187], v[4:7]
	ds_read_b128 v[192:195], v169 offset:2064
	v_mfma_f32_16x16x32_f16 v[8:11], v[136:139], v[184:187], v[8:11]
	ds_read_b128 v[196:199], v169 offset:3088
	v_mfma_f32_16x16x32_f16 v[12:15], v[140:143], v[184:187], v[12:15]
	v_mfma_f32_16x16x32_f16 v[16:19], v[144:147], v[184:187], v[16:19]
	v_mfma_f32_16x16x32_f16 v[20:23], v[132:135], v[188:191], v[20:23]
	v_mfma_f32_16x16x32_f16 v[24:27], v[136:139], v[188:191], v[24:27]
	v_mfma_f32_16x16x32_f16 v[28:31], v[140:143], v[188:191], v[28:31]
	v_mfma_f32_16x16x32_f16 v[32:35], v[144:147], v[188:191], v[32:35]
	s_waitcnt vmcnt(6) lgkmcnt(0)
	s_barrier
	s_add_i32 s53, s35, 0x6000
	s_cmp_lg_u32 s35, 0x12000
	s_cselect_b32 s53, s53, 0
	v_add_u32_e32 v168, s53, v165
	v_add_u32_e32 v169, s53, v164
	v_mfma_f32_16x16x32_f16 v[36:39], v[132:135], v[192:195], v[36:39]
	ds_read_b128 v[148:151], v168 offset:16
	ds_read_b128 v[184:187], v169 offset:16
	v_mfma_f32_16x16x32_f16 v[40:43], v[136:139], v[192:195], v[40:43]
	ds_read_b128 v[152:155], v168 offset:1040
	ds_read_b128 v[188:191], v169 offset:1040
	v_mfma_f32_16x16x32_f16 v[44:47], v[140:143], v[192:195], v[44:47]
	ds_read_b128 v[156:159], v168 offset:2064
	v_mfma_f32_16x16x32_f16 v[48:51], v[144:147], v[192:195], v[48:51]
	ds_read_b128 v[160:163], v168 offset:3088
	v_mfma_f32_16x16x32_f16 v[52:55], v[132:135], v[196:199], v[52:55]
	v_mfma_f32_16x16x32_f16 v[56:59], v[136:139], v[196:199], v[56:59]
	v_mfma_f32_16x16x32_f16 v[60:63], v[140:143], v[196:199], v[60:63]
	v_mfma_f32_16x16x32_f16 v[64:67], v[144:147], v[196:199], v[64:67]
	s_waitcnt lgkmcnt(0)
	s_mov_b32 s35, s53
	v_add_u32_e32 v169, s35, v164
	v_mfma_f32_16x16x32_f16 v[4:7], v[148:151], v[184:187], v[4:7]
	ds_read_b128 v[192:195], v169 offset:2064
	v_mfma_f32_16x16x32_f16 v[8:11], v[152:155], v[184:187], v[8:11]
	ds_read_b128 v[196:199], v169 offset:3088
	v_mfma_f32_16x16x32_f16 v[12:15], v[156:159], v[184:187], v[12:15]
	v_mfma_f32_16x16x32_f16 v[16:19], v[160:163], v[184:187], v[16:19]
	v_mfma_f32_16x16x32_f16 v[20:23], v[148:151], v[188:191], v[20:23]
	v_mfma_f32_16x16x32_f16 v[24:27], v[152:155], v[188:191], v[24:27]
	v_mfma_f32_16x16x32_f16 v[28:31], v[156:159], v[188:191], v[28:31]
	v_mfma_f32_16x16x32_f16 v[32:35], v[160:163], v[188:191], v[32:35]
	s_waitcnt vmcnt(3) lgkmcnt(0)
	s_barrier
	s_add_i32 s53, s35, 0x6000
	s_cmp_lg_u32 s35, 0x12000
	s_cselect_b32 s53, s53, 0
	v_add_u32_e32 v168, s53, v165
	v_add_u32_e32 v169, s53, v164
	v_mfma_f32_16x16x32_f16 v[36:39], v[148:151], v[192:195], v[36:39]
	ds_read_b128 v[132:135], v168 offset:16
	ds_read_b128 v[184:187], v169 offset:16
	v_mfma_f32_16x16x32_f16 v[40:43], v[152:155], v[192:195], v[40:43]
	ds_read_b128 v[136:139], v168 offset:1040
	ds_read_b128 v[188:191], v169 offset:1040
	v_mfma_f32_16x16x32_f16 v[44:47], v[156:159], v[192:195], v[44:47]
	ds_read_b128 v[140:143], v168 offset:2064
	v_mfma_f32_16x16x32_f16 v[48:51], v[160:163], v[192:195], v[48:51]
	ds_read_b128 v[144:147], v168 offset:3088
	v_mfma_f32_16x16x32_f16 v[52:55], v[148:151], v[196:199], v[52:55]
	v_mfma_f32_16x16x32_f16 v[56:59], v[152:155], v[196:199], v[56:59]
	v_mfma_f32_16x16x32_f16 v[60:63], v[156:159], v[196:199], v[60:63]
	v_mfma_f32_16x16x32_f16 v[64:67], v[160:163], v[196:199], v[64:67]
	s_waitcnt lgkmcnt(0)
	s_mov_b32 s35, s53
	v_add_u32_e32 v169, s35, v164
	v_mfma_f32_16x16x32_f16 v[4:7], v[132:135], v[184:187], v[4:7]
	ds_read_b128 v[192:195], v169 offset:2064
	v_mfma_f32_16x16x32_f16 v[8:11], v[136:139], v[184:187], v[8:11]
	ds_read_b128 v[196:199], v169 offset:3088
	v_mfma_f32_16x16x32_f16 v[12:15], v[140:143], v[184:187], v[12:15]
	v_mfma_f32_16x16x32_f16 v[16:19], v[144:147], v[184:187], v[16:19]
	v_mfma_f32_16x16x32_f16 v[20:23], v[132:135], v[188:191], v[20:23]
	v_mfma_f32_16x16x32_f16 v[24:27], v[136:139], v[188:191], v[24:27]
	v_mfma_f32_16x16x32_f16 v[28:31], v[140:143], v[188:191], v[28:31]
	v_mfma_f32_16x16x32_f16 v[32:35], v[144:147], v[188:191], v[32:35]
	s_waitcnt vmcnt(0) lgkmcnt(0)
	s_barrier
	s_add_i32 s53, s35, 0x6000
	s_cmp_lg_u32 s35, 0x12000
	s_cselect_b32 s53, s53, 0
	v_add_u32_e32 v168, s53, v165
	v_add_u32_e32 v169, s53, v164
	v_mfma_f32_16x16x32_f16 v[36:39], v[132:135], v[192:195], v[36:39]
	ds_read_b128 v[148:151], v168 offset:16
	ds_read_b128 v[184:187], v169 offset:16
	v_mfma_f32_16x16x32_f16 v[40:43], v[136:139], v[192:195], v[40:43]
	ds_read_b128 v[152:155], v168 offset:1040
	ds_read_b128 v[188:191], v169 offset:1040
	v_mfma_f32_16x16x32_f16 v[44:47], v[140:143], v[192:195], v[44:47]
	ds_read_b128 v[156:159], v168 offset:2064
	v_mfma_f32_16x16x32_f16 v[48:51], v[144:147], v[192:195], v[48:51]
	ds_read_b128 v[160:163], v168 offset:3088
	v_mfma_f32_16x16x32_f16 v[52:55], v[132:135], v[196:199], v[52:55]
	v_mfma_f32_16x16x32_f16 v[56:59], v[136:139], v[196:199], v[56:59]
	v_mfma_f32_16x16x32_f16 v[60:63], v[140:143], v[196:199], v[60:63]
	v_mfma_f32_16x16x32_f16 v[64:67], v[144:147], v[196:199], v[64:67]
	s_waitcnt lgkmcnt(0)
	s_mov_b32 s35, s53
	v_add_u32_e32 v169, s35, v164
	v_mfma_f32_16x16x32_f16 v[4:7], v[148:151], v[184:187], v[4:7]
	ds_read_b128 v[192:195], v169 offset:2064
	v_mfma_f32_16x16x32_f16 v[8:11], v[152:155], v[184:187], v[8:11]
	ds_read_b128 v[196:199], v169 offset:3088
	v_mfma_f32_16x16x32_f16 v[12:15], v[156:159], v[184:187], v[12:15]
	v_mfma_f32_16x16x32_f16 v[16:19], v[160:163], v[184:187], v[16:19]
	v_mfma_f32_16x16x32_f16 v[20:23], v[148:151], v[188:191], v[20:23]
	v_mfma_f32_16x16x32_f16 v[24:27], v[152:155], v[188:191], v[24:27]
	v_mfma_f32_16x16x32_f16 v[28:31], v[156:159], v[188:191], v[28:31]
	v_mfma_f32_16x16x32_f16 v[32:35], v[160:163], v[188:191], v[32:35]
	s_waitcnt lgkmcnt(0)
	s_barrier
	v_mfma_f32_16x16x32_f16 v[36:39], v[148:151], v[192:195], v[36:39]
	v_mfma_f32_16x16x32_f16 v[40:43], v[152:155], v[192:195], v[40:43]
	v_mfma_f32_16x16x32_f16 v[44:47], v[156:159], v[192:195], v[44:47]
	v_mfma_f32_16x16x32_f16 v[48:51], v[160:163], v[192:195], v[48:51]
	v_mfma_f32_16x16x32_f16 v[52:55], v[148:151], v[196:199], v[52:55]
	v_mfma_f32_16x16x32_f16 v[56:59], v[152:155], v[196:199], v[56:59]
	v_mfma_f32_16x16x32_f16 v[60:63], v[156:159], v[196:199], v[60:63]
	v_mfma_f32_16x16x32_f16 v[64:67], v[160:163], v[196:199], v[64:67]
	s_sub_u32 s77, s34, 0x1000
	s_lshr_b32 s77, s77, 12
	s_add_u32 s77, s77, 1
	s_cmp_lt_u32 s34, 0x1000
	s_cselect_b32 s77, 0, s77
	s_mul_i32 s77, s77, 0x6000
	s_add_u32 s68, s44, s77
	s_addc_u32 s69, s45, 0
	s_add_u32 s68, s68, 0xfa10600
	s_addc_u32 s69, s69, 0
	s_lshl_b32 s82, s34, 11
	s_add_u32 s80, s46, s82
	s_addc_u32 s81, s47, 0
	s_lshl_b32 s82, s30, 1
	s_add_u32 s80, s80, s82
	s_addc_u32 s81, s81, 0
	v_and_b32_e32 v172, 15, v200
	v_bfe_u32 v173, v200, 4, 2
	v_bfe_u32 v174, v200, 6, 1
	v_bfe_u32 v175, v200, 7, 2
	v_lshlrev_b32_e32 v176, 6, v174
	v_lshl_or_b32 v176, v173, 2, v176
	v_lshl_or_b32 v175, v175, 6, v172
	v_lshlrev_b32_e32 v175, 11, v175
	v_lshl_add_u32 v177, v176, 1, v175
	v_add_u32_e32 v176, s30, v176
	v_lshlrev_b32_e32 v176, 2, v176
	global_load_dwordx4 v[132:135], v176, s[68:69]
	global_load_dwordx4 v[136:139], v176, s[68:69] offset:64
	global_load_dwordx4 v[140:143], v176, s[68:69] offset:128
	global_load_dwordx4 v[144:147], v176, s[68:69] offset:192
	v_mov_b32_e32 v178, v177
	global_load_dwordx2 v[184:185], v178, s[80:81]
	global_load_dwordx2 v[186:187], v178, s[80:81] offset:32
	global_load_dwordx2 v[188:189], v178, s[80:81] offset:64
	global_load_dwordx2 v[190:191], v178, s[80:81] offset:96
	v_add_u32_e32 v178, 0x8000, v178
	global_load_dwordx2 v[192:193], v178, s[80:81]
	global_load_dwordx2 v[194:195], v178, s[80:81] offset:32
	global_load_dwordx2 v[196:197], v178, s[80:81] offset:64
	global_load_dwordx2 v[198:199], v178, s[80:81] offset:96
	s_waitcnt vmcnt(7)
	v_cvt_f32_f16_e32 v164, v184
	v_cvt_f32_f16_sdwa v165, v184 dst_sel:DWORD dst_unused:UNUSED_PAD src0_sel:WORD_1
	v_cvt_f32_f16_e32 v166, v185
	v_cvt_f32_f16_sdwa v167, v185 dst_sel:DWORD dst_unused:UNUSED_PAD src0_sel:WORD_1
	v_pk_mul_f32 v[164:165], v[164:165], s[84:85] op_sel_hi:[1,0]
	v_pk_mul_f32 v[166:167], v[166:167], s[84:85] op_sel_hi:[1,0]
	v_pk_fma_f32 v[4:5], v[4:5], v[132:133], v[164:165]
	v_pk_fma_f32 v[6:7], v[6:7], v[134:135], v[166:167]
	v_cvt_pk_f16_f32 v172, v4, v5
	v_cvt_pk_f16_f32 v173, v6, v7
	global_store_dwordx2 v177, v[172:173], s[80:81]
	s_waitcnt vmcnt(7)
	v_cvt_f32_f16_e32 v164, v186
	v_cvt_f32_f16_sdwa v165, v186 dst_sel:DWORD dst_unused:UNUSED_PAD src0_sel:WORD_1
	v_cvt_f32_f16_e32 v166, v187
	v_cvt_f32_f16_sdwa v167, v187 dst_sel:DWORD dst_unused:UNUSED_PAD src0_sel:WORD_1
	v_pk_mul_f32 v[164:165], v[164:165], s[84:85] op_sel_hi:[1,0]
	v_pk_mul_f32 v[166:167], v[166:167], s[84:85] op_sel_hi:[1,0]
	v_pk_fma_f32 v[8:9], v[8:9], v[136:137], v[164:165]
	v_pk_fma_f32 v[10:11], v[10:11], v[138:139], v[166:167]
	v_cvt_pk_f16_f32 v174, v8, v9
	v_cvt_pk_f16_f32 v175, v10, v11
	global_store_dwordx2 v177, v[174:175], s[80:81] offset:32
	s_waitcnt vmcnt(7)
	v_cvt_f32_f16_e32 v164, v188
	v_cvt_f32_f16_sdwa v165, v188 dst_sel:DWORD dst_unused:UNUSED_PAD src0_sel:WORD_1
	v_cvt_f32_f16_e32 v166, v189
	v_cvt_f32_f16_sdwa v167, v189 dst_sel:DWORD dst_unused:UNUSED_PAD src0_sel:WORD_1
	v_pk_mul_f32 v[164:165], v[164:165], s[84:85] op_sel_hi:[1,0]
	v_pk_mul_f32 v[166:167], v[166:167], s[84:85] op_sel_hi:[1,0]
	v_pk_fma_f32 v[12:13], v[12:13], v[140:141], v[164:165]
	v_pk_fma_f32 v[14:15], v[14:15], v[142:143], v[166:167]
	v_cvt_pk_f16_f32 v172, v12, v13
	v_cvt_pk_f16_f32 v173, v14, v15
	global_store_dwordx2 v177, v[172:173], s[80:81] offset:64
	s_waitcnt vmcnt(7)
	v_cvt_f32_f16_e32 v164, v190
	v_cvt_f32_f16_sdwa v165, v190 dst_sel:DWORD dst_unused:UNUSED_PAD src0_sel:WORD_1
	v_cvt_f32_f16_e32 v166, v191
	v_cvt_f32_f16_sdwa v167, v191 dst_sel:DWORD dst_unused:UNUSED_PAD src0_sel:WORD_1
	v_pk_mul_f32 v[164:165], v[164:165], s[84:85] op_sel_hi:[1,0]
	v_pk_mul_f32 v[166:167], v[166:167], s[84:85] op_sel_hi:[1,0]
	v_pk_fma_f32 v[16:17], v[16:17], v[144:145], v[164:165]
	v_pk_fma_f32 v[18:19], v[18:19], v[146:147], v[166:167]
	v_cvt_pk_f16_f32 v174, v16, v17
	v_cvt_pk_f16_f32 v175, v18, v19
	global_store_dwordx2 v177, v[174:175], s[80:81] offset:96
	v_add_u32_e32 v177, 0x8000, v177
	v_add_u32_e32 v178, 0x8000, v178
	global_load_dwordx2 v[184:185], v178, s[80:81]
	global_load_dwordx2 v[186:187], v178, s[80:81] offset:32
	global_load_dwordx2 v[188:189], v178, s[80:81] offset:64
	global_load_dwordx2 v[190:191], v178, s[80:81] offset:96
	s_waitcnt vmcnt(11)
	v_cvt_f32_f16_e32 v164, v192
	v_cvt_f32_f16_sdwa v165, v192 dst_sel:DWORD dst_unused:UNUSED_PAD src0_sel:WORD_1
	v_cvt_f32_f16_e32 v166, v193
	v_cvt_f32_f16_sdwa v167, v193 dst_sel:DWORD dst_unused:UNUSED_PAD src0_sel:WORD_1
	v_pk_mul_f32 v[164:165], v[164:165], s[84:85] op_sel_hi:[1,0]
	v_pk_mul_f32 v[166:167], v[166:167], s[84:85] op_sel_hi:[1,0]
	v_pk_fma_f32 v[20:21], v[20:21], v[132:133], v[164:165]
	v_pk_fma_f32 v[22:23], v[22:23], v[134:135], v[166:167]
	v_cvt_pk_f16_f32 v172, v20, v21
	v_cvt_pk_f16_f32 v173, v22, v23
	global_store_dwordx2 v177, v[172:173], s[80:81]
	s_waitcnt vmcnt(11)
	v_cvt_f32_f16_e32 v164, v194
	v_cvt_f32_f16_sdwa v165, v194 dst_sel:DWORD dst_unused:UNUSED_PAD src0_sel:WORD_1
	v_cvt_f32_f16_e32 v166, v195
	v_cvt_f32_f16_sdwa v167, v195 dst_sel:DWORD dst_unused:UNUSED_PAD src0_sel:WORD_1
	v_pk_mul_f32 v[164:165], v[164:165], s[84:85] op_sel_hi:[1,0]
	v_pk_mul_f32 v[166:167], v[166:167], s[84:85] op_sel_hi:[1,0]
	v_pk_fma_f32 v[24:25], v[24:25], v[136:137], v[164:165]
	v_pk_fma_f32 v[26:27], v[26:27], v[138:139], v[166:167]
	v_cvt_pk_f16_f32 v174, v24, v25
	v_cvt_pk_f16_f32 v175, v26, v27
	global_store_dwordx2 v177, v[174:175], s[80:81] offset:32
	s_waitcnt vmcnt(11)
	v_cvt_f32_f16_e32 v164, v196
	v_cvt_f32_f16_sdwa v165, v196 dst_sel:DWORD dst_unused:UNUSED_PAD src0_sel:WORD_1
	v_cvt_f32_f16_e32 v166, v197
	v_cvt_f32_f16_sdwa v167, v197 dst_sel:DWORD dst_unused:UNUSED_PAD src0_sel:WORD_1
	v_pk_mul_f32 v[164:165], v[164:165], s[84:85] op_sel_hi:[1,0]
	v_pk_mul_f32 v[166:167], v[166:167], s[84:85] op_sel_hi:[1,0]
	v_pk_fma_f32 v[28:29], v[28:29], v[140:141], v[164:165]
	v_pk_fma_f32 v[30:31], v[30:31], v[142:143], v[166:167]
	v_cvt_pk_f16_f32 v172, v28, v29
	v_cvt_pk_f16_f32 v173, v30, v31
	global_store_dwordx2 v177, v[172:173], s[80:81] offset:64
	s_waitcnt vmcnt(11)
	v_cvt_f32_f16_e32 v164, v198
	v_cvt_f32_f16_sdwa v165, v198 dst_sel:DWORD dst_unused:UNUSED_PAD src0_sel:WORD_1
	v_cvt_f32_f16_e32 v166, v199
	v_cvt_f32_f16_sdwa v167, v199 dst_sel:DWORD dst_unused:UNUSED_PAD src0_sel:WORD_1
	v_pk_mul_f32 v[164:165], v[164:165], s[84:85] op_sel_hi:[1,0]
	v_pk_mul_f32 v[166:167], v[166:167], s[84:85] op_sel_hi:[1,0]
	v_pk_fma_f32 v[32:33], v[32:33], v[144:145], v[164:165]
	v_pk_fma_f32 v[34:35], v[34:35], v[146:147], v[166:167]
	v_cvt_pk_f16_f32 v174, v32, v33
	v_cvt_pk_f16_f32 v175, v34, v35
	global_store_dwordx2 v177, v[174:175], s[80:81] offset:96
	v_add_u32_e32 v177, 0x8000, v177
	v_add_u32_e32 v178, 0x8000, v178
	global_load_dwordx2 v[192:193], v178, s[80:81]
	global_load_dwordx2 v[194:195], v178, s[80:81] offset:32
	global_load_dwordx2 v[196:197], v178, s[80:81] offset:64
	global_load_dwordx2 v[198:199], v178, s[80:81] offset:96
	s_waitcnt vmcnt(11)
	v_cvt_f32_f16_e32 v164, v184
	v_cvt_f32_f16_sdwa v165, v184 dst_sel:DWORD dst_unused:UNUSED_PAD src0_sel:WORD_1
	v_cvt_f32_f16_e32 v166, v185
	v_cvt_f32_f16_sdwa v167, v185 dst_sel:DWORD dst_unused:UNUSED_PAD src0_sel:WORD_1
	v_pk_mul_f32 v[164:165], v[164:165], s[84:85] op_sel_hi:[1,0]
	v_pk_mul_f32 v[166:167], v[166:167], s[84:85] op_sel_hi:[1,0]
	v_pk_fma_f32 v[36:37], v[36:37], v[132:133], v[164:165]
	v_pk_fma_f32 v[38:39], v[38:39], v[134:135], v[166:167]
	v_cvt_pk_f16_f32 v172, v36, v37
	v_cvt_pk_f16_f32 v173, v38, v39
	global_store_dwordx2 v177, v[172:173], s[80:81]
	s_waitcnt vmcnt(11)
	v_cvt_f32_f16_e32 v164, v186
	v_cvt_f32_f16_sdwa v165, v186 dst_sel:DWORD dst_unused:UNUSED_PAD src0_sel:WORD_1
	v_cvt_f32_f16_e32 v166, v187
	v_cvt_f32_f16_sdwa v167, v187 dst_sel:DWORD dst_unused:UNUSED_PAD src0_sel:WORD_1
	v_pk_mul_f32 v[164:165], v[164:165], s[84:85] op_sel_hi:[1,0]
	v_pk_mul_f32 v[166:167], v[166:167], s[84:85] op_sel_hi:[1,0]
	v_pk_fma_f32 v[40:41], v[40:41], v[136:137], v[164:165]
	v_pk_fma_f32 v[42:43], v[42:43], v[138:139], v[166:167]
	v_cvt_pk_f16_f32 v174, v40, v41
	v_cvt_pk_f16_f32 v175, v42, v43
	global_store_dwordx2 v177, v[174:175], s[80:81] offset:32
	s_waitcnt vmcnt(11)
	v_cvt_f32_f16_e32 v164, v188
	v_cvt_f32_f16_sdwa v165, v188 dst_sel:DWORD dst_unused:UNUSED_PAD src0_sel:WORD_1
	v_cvt_f32_f16_e32 v166, v189
	v_cvt_f32_f16_sdwa v167, v189 dst_sel:DWORD dst_unused:UNUSED_PAD src0_sel:WORD_1
	v_pk_mul_f32 v[164:165], v[164:165], s[84:85] op_sel_hi:[1,0]
	v_pk_mul_f32 v[166:167], v[166:167], s[84:85] op_sel_hi:[1,0]
	v_pk_fma_f32 v[44:45], v[44:45], v[140:141], v[164:165]
	v_pk_fma_f32 v[46:47], v[46:47], v[142:143], v[166:167]
	v_cvt_pk_f16_f32 v172, v44, v45
	v_cvt_pk_f16_f32 v173, v46, v47
	global_store_dwordx2 v177, v[172:173], s[80:81] offset:64
	s_waitcnt vmcnt(11)
	v_cvt_f32_f16_e32 v164, v190
	v_cvt_f32_f16_sdwa v165, v190 dst_sel:DWORD dst_unused:UNUSED_PAD src0_sel:WORD_1
	v_cvt_f32_f16_e32 v166, v191
	v_cvt_f32_f16_sdwa v167, v191 dst_sel:DWORD dst_unused:UNUSED_PAD src0_sel:WORD_1
	v_pk_mul_f32 v[164:165], v[164:165], s[84:85] op_sel_hi:[1,0]
	v_pk_mul_f32 v[166:167], v[166:167], s[84:85] op_sel_hi:[1,0]
	v_pk_fma_f32 v[48:49], v[48:49], v[144:145], v[164:165]
	v_pk_fma_f32 v[50:51], v[50:51], v[146:147], v[166:167]
	v_cvt_pk_f16_f32 v174, v48, v49
	v_cvt_pk_f16_f32 v175, v50, v51
	global_store_dwordx2 v177, v[174:175], s[80:81] offset:96
	v_add_u32_e32 v177, 0x8000, v177
	s_waitcnt vmcnt(7)
	v_cvt_f32_f16_e32 v164, v192
	v_cvt_f32_f16_sdwa v165, v192 dst_sel:DWORD dst_unused:UNUSED_PAD src0_sel:WORD_1
	v_cvt_f32_f16_e32 v166, v193
	v_cvt_f32_f16_sdwa v167, v193 dst_sel:DWORD dst_unused:UNUSED_PAD src0_sel:WORD_1
	v_pk_mul_f32 v[164:165], v[164:165], s[84:85] op_sel_hi:[1,0]
	v_pk_mul_f32 v[166:167], v[166:167], s[84:85] op_sel_hi:[1,0]
	v_pk_fma_f32 v[52:53], v[52:53], v[132:133], v[164:165]
	v_pk_fma_f32 v[54:55], v[54:55], v[134:135], v[166:167]
	v_cvt_pk_f16_f32 v172, v52, v53
	v_cvt_pk_f16_f32 v173, v54, v55
	global_store_dwordx2 v177, v[172:173], s[80:81]
	s_waitcnt vmcnt(7)
	v_cvt_f32_f16_e32 v164, v194
	v_cvt_f32_f16_sdwa v165, v194 dst_sel:DWORD dst_unused:UNUSED_PAD src0_sel:WORD_1
	v_cvt_f32_f16_e32 v166, v195
	v_cvt_f32_f16_sdwa v167, v195 dst_sel:DWORD dst_unused:UNUSED_PAD src0_sel:WORD_1
	v_pk_mul_f32 v[164:165], v[164:165], s[84:85] op_sel_hi:[1,0]
	v_pk_mul_f32 v[166:167], v[166:167], s[84:85] op_sel_hi:[1,0]
	v_pk_fma_f32 v[56:57], v[56:57], v[136:137], v[164:165]
	v_pk_fma_f32 v[58:59], v[58:59], v[138:139], v[166:167]
	v_cvt_pk_f16_f32 v174, v56, v57
	v_cvt_pk_f16_f32 v175, v58, v59
	global_store_dwordx2 v177, v[174:175], s[80:81] offset:32
	s_waitcnt vmcnt(7)
	v_cvt_f32_f16_e32 v164, v196
	v_cvt_f32_f16_sdwa v165, v196 dst_sel:DWORD dst_unused:UNUSED_PAD src0_sel:WORD_1
	v_cvt_f32_f16_e32 v166, v197
	v_cvt_f32_f16_sdwa v167, v197 dst_sel:DWORD dst_unused:UNUSED_PAD src0_sel:WORD_1
	v_pk_mul_f32 v[164:165], v[164:165], s[84:85] op_sel_hi:[1,0]
	v_pk_mul_f32 v[166:167], v[166:167], s[84:85] op_sel_hi:[1,0]
	v_pk_fma_f32 v[60:61], v[60:61], v[140:141], v[164:165]
	v_pk_fma_f32 v[62:63], v[62:63], v[142:143], v[166:167]
	v_cvt_pk_f16_f32 v172, v60, v61
	v_cvt_pk_f16_f32 v173, v62, v63
	global_store_dwordx2 v177, v[172:173], s[80:81] offset:64
	s_waitcnt vmcnt(7)
	v_cvt_f32_f16_e32 v164, v198
	v_cvt_f32_f16_sdwa v165, v198 dst_sel:DWORD dst_unused:UNUSED_PAD src0_sel:WORD_1
	v_cvt_f32_f16_e32 v166, v199
	v_cvt_f32_f16_sdwa v167, v199 dst_sel:DWORD dst_unused:UNUSED_PAD src0_sel:WORD_1
	v_pk_mul_f32 v[164:165], v[164:165], s[84:85] op_sel_hi:[1,0]
	v_pk_mul_f32 v[166:167], v[166:167], s[84:85] op_sel_hi:[1,0]
	v_pk_fma_f32 v[64:65], v[64:65], v[144:145], v[164:165]
	v_pk_fma_f32 v[66:67], v[66:67], v[146:147], v[166:167]
	v_cvt_pk_f16_f32 v174, v64, v65
	v_cvt_pk_f16_f32 v175, v66, v67
	global_store_dwordx2 v177, v[174:175], s[80:81] offset:96
	s_nop 1
	s_add_i32 s24, s24, s64
	s_cmpk_gt_i32 s24, 0x27f
	s_cbranch_scc1 .LBB0_759
	s_branch .LBB0_700
